# c3 + A/B fragment quads re-homed to accumulator VGPR bank phase in 5 GEMM loops
# speedup vs baseline: 1.0173x; 1.0088x over previous
; #define PG8_STAGE(bufoff, gbase, voff) do { _Pragma("unroll") for (int _i = 0; _i < 2; ++_i) \
;         __builtin_amdgcn_global_load_lds((const unsigned*)((const char*)(gbase) + (voff)[_i]), (LAS unsigned*)(lds + (bufoff) + ldsw + _i * 8192), 16, 0, 0); } while (0)
; #define PG8_LDA(dst, b, h) do { _Pragma("unroll") for (int m = 0; m < 4; ++m) _Pragma("unroll") for (int k = 0; k < 2; ++k) dst[m][k] = *(const LAS bf16x8*)(lds + PG8_SA(b, h) + aoff + m * 2048 + k * 1024); } while (0)
; #define PG8_LDB(dst, b, h) do { _Pragma("unroll") for (int n = 0; n < 2; ++n) _Pragma("unroll") for (int k = 0; k < 2; ++k) dst[n][k] = *(const LAS bf16x8*)(lds + PG8_SB(b, h) + boff + n * 2048 + k * 1024); } while (0)
; #define PG8_MMA(ai, bj, At, Bt) do { __builtin_amdgcn_s_setprio(1); _Pragma("unroll") for (int m = 0; m < 4; ++m) _Pragma("unroll") for (int n = 0; n < 2; ++n) _Pragma("unroll") for (int k = 0; k < 2; ++k) \
;         acc[ai][bj][m][n] = __builtin_amdgcn_mfma_f32_16x16x32_bf16(Bt[n][k], At[m][k], acc[ai][bj][m][n], 0, 0, 0); __builtin_amdgcn_s_setprio(0); } while (0)
; #define PG8_WAIT_V(n) asm volatile("s_waitcnt vmcnt(" #n ")" ::: "memory")
; #define PG8_WAIT_L(n) asm volatile("s_waitcnt lgkmcnt(" #n ")" ::: "memory")
; #define PG8_BAR __builtin_amdgcn_s_barrier()
; template <class Epi>
; __device__ __forceinline__ void gemm_phase(LAS unsigned char* lds, const Gemm g, const StaticOrder& S, const Epi& E) {
;     ...
;             const bool last = (t == nt - 2);
;             const char* a1 = cA + (size_t)(t + 1) * kstep;
;             const char* a2 = last ? nA : cA + (size_t)(t + 2) * kstep; const char* b2 = last ? nB : cB + (size_t)(t + 2) * kstep;
;             const char* a3 = a2 + kstep; const char* b3 = b2 + kstep;
;             if constexpr (Epi::MIDK > 0) { if (t == Epi::MIDK) E.mid(acc, cur, wr, wc, fr, fq); }
;             PG8_LDB(B0, 0, 0); PG8_LDB(B1, 0, 1); PG8_SCHED; PG8_LDA(At, 0, 0); PG8_STAGE(PG8_SA(1, 1), a1 + hstep, voffA);
;             PG8_WAIT_V(8); PG8_WAIT_L(0); PG8_BAR; PG8_MMA(0, 0, At, B0); PG8_MMA(0, 1, At, B1); PG8_BAR; PG8_SCHED;
;             PG8_LDA(At, 0, 1); PG8_STAGE(PG8_SB(0, 0), b2, voffB); PG8_STAGE(PG8_SB(0, 1), b2 + hstep, voffB); PG8_STAGE(PG8_SA(0, 0), a2, voffA);
;             PG8_WAIT_V(8); PG8_WAIT_L(0); PG8_BAR; PG8_MMA(1, 0, At, B0); PG8_MMA(1, 1, At, B1); PG8_BAR; PG8_SCHED;
.LBB0_134:
	ds_read_b128 v[158:161], v150
	ds_read_b128 v[162:165], v150 offset:1024
	ds_read_b128 v[166:169], v150 offset:2048
	ds_read_b128 v[174:177], v150 offset:3072
	ds_read_b128 v[178:181], v151
	ds_read_b128 v[182:185], v151 offset:1024
	ds_read_b128 v[186:189], v151 offset:2048
	ds_read_b128 v[190:193], v151 offset:3072
	s_add_u32 s66, s64, 0xfffc0080
	s_addc_u32 s67, s65, -1
	s_cmp_eq_u32 s92, 12
	s_cselect_b32 s69, s87, s67
	s_cselect_b32 s68, s88, s66
	s_cselect_b32 s67, s47, s91
	s_cselect_b32 s66, s89, s90
	s_add_i32 m0, s61, 0xc000
	ds_read_b128 v[194:197], v152
	ds_read_b128 v[198:201], v152 offset:1024
	ds_read_b128 v[202:205], v152 offset:2048
	ds_read_b128 v[206:209], v152 offset:3072
	ds_read_b128 v[210:213], v152 offset:4096
	ds_read_b128 v[214:217], v152 offset:5120
	ds_read_b128 v[218:221], v152 offset:6144
	ds_read_b128 v[222:225], v152 offset:7168
	global_load_lds_dwordx4 v140, s[64:65]
	s_add_i32 m0, s61, 0xe000
	s_nop 0
	global_load_lds_dwordx4 v142, s[64:65]
	s_waitcnt vmcnt(8)
	s_waitcnt lgkmcnt(0)
	s_setprio 1
	s_barrier
	v_mfma_f32_16x16x32_bf16 v[126:129], v[158:161], v[194:197], v[126:129]
	v_mfma_f32_16x16x32_bf16 v[118:121], v[166:169], v[194:197], v[118:121]
	v_mfma_f32_16x16x32_bf16 v[110:113], v[158:161], v[202:205], v[110:113]
	v_mfma_f32_16x16x32_bf16 v[102:105], v[166:169], v[202:205], v[102:105]
	v_mfma_f32_16x16x32_bf16 v[94:97], v[158:161], v[210:213], v[94:97]
	v_mfma_f32_16x16x32_bf16 v[86:89], v[166:169], v[210:213], v[86:89]
	v_mfma_f32_16x16x32_bf16 v[78:81], v[158:161], v[218:221], v[78:81]
	v_mfma_f32_16x16x32_bf16 v[70:73], v[166:169], v[218:221], v[70:73]
	v_mfma_f32_16x16x32_bf16 v[126:129], v[162:165], v[198:201], v[126:129]
	v_mfma_f32_16x16x32_bf16 v[118:121], v[174:177], v[198:201], v[118:121]
	v_mfma_f32_16x16x32_bf16 v[110:113], v[162:165], v[206:209], v[110:113]
	v_mfma_f32_16x16x32_bf16 v[102:105], v[174:177], v[206:209], v[102:105]
	v_mfma_f32_16x16x32_bf16 v[94:97], v[162:165], v[214:217], v[94:97]
	v_mfma_f32_16x16x32_bf16 v[86:89], v[174:177], v[214:217], v[86:89]
	v_mfma_f32_16x16x32_bf16 v[78:81], v[162:165], v[222:225], v[78:81]
	v_mfma_f32_16x16x32_bf16 v[70:73], v[174:177], v[222:225], v[70:73]
	v_mfma_f32_16x16x32_bf16 v[122:125], v[178:181], v[194:197], v[122:125]
	v_mfma_f32_16x16x32_bf16 v[114:117], v[186:189], v[194:197], v[114:117]
	v_mfma_f32_16x16x32_bf16 v[106:109], v[178:181], v[202:205], v[106:109]
	v_mfma_f32_16x16x32_bf16 v[98:101], v[186:189], v[202:205], v[98:101]
	v_mfma_f32_16x16x32_bf16 v[90:93], v[178:181], v[210:213], v[90:93]
	v_mfma_f32_16x16x32_bf16 v[82:85], v[186:189], v[210:213], v[82:85]
	v_mfma_f32_16x16x32_bf16 v[74:77], v[178:181], v[218:221], v[74:77]
	v_mfma_f32_16x16x32_bf16 v[66:69], v[186:189], v[218:221], v[66:69]
	v_mfma_f32_16x16x32_bf16 v[122:125], v[182:185], v[198:201], v[122:125]
	v_mfma_f32_16x16x32_bf16 v[114:117], v[190:193], v[198:201], v[114:117]
	v_mfma_f32_16x16x32_bf16 v[106:109], v[182:185], v[206:209], v[106:109]
	v_mfma_f32_16x16x32_bf16 v[98:101], v[190:193], v[206:209], v[98:101]
	v_mfma_f32_16x16x32_bf16 v[90:93], v[182:185], v[214:217], v[90:93]
	v_mfma_f32_16x16x32_bf16 v[82:85], v[190:193], v[214:217], v[82:85]
	v_mfma_f32_16x16x32_bf16 v[74:77], v[182:185], v[222:225], v[74:77]
	v_mfma_f32_16x16x32_bf16 v[66:69], v[190:193], v[222:225], v[66:69]
	s_barrier
	s_setprio 0
	s_add_u32 s98, s66, s8
	s_addc_u32 s99, s67, s9
	s_add_u32 s100, s68, s8
	s_addc_u32 s101, s69, s9
	s_add_i32 s93, s83, s6
	s_mov_b32 m0, s93
	ds_read_b128 v[194:197], v152 offset:16384
	ds_read_b128 v[198:201], v152 offset:17408
	ds_read_b128 v[202:205], v152 offset:18432
	ds_read_b128 v[206:209], v152 offset:19456
	ds_read_b128 v[210:213], v152 offset:20480
	ds_read_b128 v[214:217], v152 offset:21504
	ds_read_b128 v[218:221], v152 offset:22528
	ds_read_b128 v[222:225], v152 offset:23552
	global_load_lds_dwordx4 v132, s[66:67]
	s_add_i32 m0, s93, 0x2000
	s_add_u32 s94, s66, 0x40000
	s_addc_u32 s95, s67, 0
	s_add_i32 s93, s84, s6
	global_load_lds_dwordx4 v136, s[66:67]
	s_mov_b32 m0, s93
	s_nop 0
	global_load_lds_dwordx4 v132, s[94:95]
	s_add_i32 m0, s93, 0x2000
	s_nop 0
	global_load_lds_dwordx4 v136, s[94:95]
	s_mov_b32 m0, s61
	s_nop 0
	global_load_lds_dwordx4 v130, s[68:69]
	s_mov_b32 m0, s63
	s_nop 0
	global_load_lds_dwordx4 v134, s[68:69]
	s_waitcnt vmcnt(8)
	s_waitcnt lgkmcnt(0)
	s_setprio 1
	s_barrier
	v_mfma_f32_16x16x32_bf16 v[62:65], v[158:161], v[194:197], v[62:65]
	v_mfma_f32_16x16x32_bf16 v[54:57], v[166:169], v[194:197], v[54:57]
	v_mfma_f32_16x16x32_bf16 v[46:49], v[158:161], v[202:205], v[46:49]
	v_mfma_f32_16x16x32_bf16 v[38:41], v[166:169], v[202:205], v[38:41]
	v_mfma_f32_16x16x32_bf16 v[30:33], v[158:161], v[210:213], v[30:33]
	v_mfma_f32_16x16x32_bf16 v[22:25], v[166:169], v[210:213], v[22:25]
	v_mfma_f32_16x16x32_bf16 v[14:17], v[158:161], v[218:221], v[14:17]
	v_mfma_f32_16x16x32_bf16 v[6:9], v[166:169], v[218:221], v[6:9]
	v_mfma_f32_16x16x32_bf16 v[62:65], v[162:165], v[198:201], v[62:65]
	v_mfma_f32_16x16x32_bf16 v[54:57], v[174:177], v[198:201], v[54:57]
	v_mfma_f32_16x16x32_bf16 v[46:49], v[162:165], v[206:209], v[46:49]
	v_mfma_f32_16x16x32_bf16 v[38:41], v[174:177], v[206:209], v[38:41]
	v_mfma_f32_16x16x32_bf16 v[30:33], v[162:165], v[214:217], v[30:33]
	v_mfma_f32_16x16x32_bf16 v[22:25], v[174:177], v[214:217], v[22:25]
	v_mfma_f32_16x16x32_bf16 v[14:17], v[162:165], v[222:225], v[14:17]
	v_mfma_f32_16x16x32_bf16 v[6:9], v[174:177], v[222:225], v[6:9]
	v_mfma_f32_16x16x32_bf16 v[58:61], v[178:181], v[194:197], v[58:61]
	v_mfma_f32_16x16x32_bf16 v[50:53], v[186:189], v[194:197], v[50:53]
	v_mfma_f32_16x16x32_bf16 v[42:45], v[178:181], v[202:205], v[42:45]
	v_mfma_f32_16x16x32_bf16 v[34:37], v[186:189], v[202:205], v[34:37]
	v_mfma_f32_16x16x32_bf16 v[26:29], v[178:181], v[210:213], v[26:29]
	v_mfma_f32_16x16x32_bf16 v[18:21], v[186:189], v[210:213], v[18:21]
	v_mfma_f32_16x16x32_bf16 v[10:13], v[178:181], v[218:221], v[10:13]
	v_mfma_f32_16x16x32_bf16 v[2:5], v[186:189], v[218:221], v[2:5]
	v_mfma_f32_16x16x32_bf16 v[58:61], v[182:185], v[198:201], v[58:61]
	v_mfma_f32_16x16x32_bf16 v[50:53], v[190:193], v[198:201], v[50:53]
	v_mfma_f32_16x16x32_bf16 v[42:45], v[182:185], v[206:209], v[42:45]
	v_mfma_f32_16x16x32_bf16 v[34:37], v[190:193], v[206:209], v[34:37]
	v_mfma_f32_16x16x32_bf16 v[26:29], v[182:185], v[214:217], v[26:29]
	v_mfma_f32_16x16x32_bf16 v[18:21], v[190:193], v[214:217], v[18:21]
	v_mfma_f32_16x16x32_bf16 v[10:13], v[182:185], v[222:225], v[10:13]
	v_mfma_f32_16x16x32_bf16 v[2:5], v[190:193], v[222:225], v[2:5]
	s_barrier
; #define PG8_STAGE(bufoff, gbase, voff) do { _Pragma("unroll") for (int _i = 0; _i < 2; ++_i) \
;         __builtin_amdgcn_global_load_lds((const unsigned*)((const char*)(gbase) + (voff)[_i]), (LAS unsigned*)(lds + (bufoff) + ldsw + _i * 8192), 16, 0, 0); } while (0)
; #define PG8_LDA(dst, b, h) do { _Pragma("unroll") for (int m = 0; m < 4; ++m) _Pragma("unroll") for (int k = 0; k < 2; ++k) dst[m][k] = *(const LAS bf16x8*)(lds + PG8_SA(b, h) + aoff + m * 2048 + k * 1024); } while (0)
; #define PG8_LDB(dst, b, h) do { _Pragma("unroll") for (int n = 0; n < 2; ++n) _Pragma("unroll") for (int k = 0; k < 2; ++k) dst[n][k] = *(const LAS bf16x8*)(lds + PG8_SB(b, h) + boff + n * 2048 + k * 1024); } while (0)
; #define PG8_MMA(ai, bj, At, Bt) do { __builtin_amdgcn_s_setprio(1); _Pragma("unroll") for (int m = 0; m < 4; ++m) _Pragma("unroll") for (int n = 0; n < 2; ++n) _Pragma("unroll") for (int k = 0; k < 2; ++k) \
;         acc[ai][bj][m][n] = __builtin_amdgcn_mfma_f32_16x16x32_bf16(Bt[n][k], At[m][k], acc[ai][bj][m][n], 0, 0, 0); __builtin_amdgcn_s_setprio(0); } while (0)
; #define PG8_WAIT_V(n) asm volatile("s_waitcnt vmcnt(" #n ")" ::: "memory")
; #define PG8_WAIT_L(n) asm volatile("s_waitcnt lgkmcnt(" #n ")" ::: "memory")
; #define PG8_BAR __builtin_amdgcn_s_barrier()
; #define PG8_SCHED __builtin_amdgcn_sched_barrier(0)
; template <class Epi>
; __device__ __forceinline__ void gemm_phase(LAS unsigned char* lds, const Gemm g, const StaticOrder& S, const Epi& E) {
;     ...
;             PG8_LDB(B0, 1, 0); PG8_LDB(B1, 1, 1); PG8_SCHED; PG8_LDA(At, 1, 0); PG8_STAGE(PG8_SA(0, 1), a2 + hstep, voffA);
;             PG8_WAIT_V(8); PG8_WAIT_L(0); PG8_BAR; PG8_MMA(0, 0, At, B0); PG8_MMA(0, 1, At, B1); PG8_BAR; PG8_SCHED;
;             PG8_LDA(At, 1, 1); PG8_STAGE(PG8_SB(1, 0), b3, voffB); PG8_STAGE(PG8_SB(1, 1), b3 + hstep, voffB); PG8_STAGE(PG8_SA(1, 0), a3, voffA);
;             PG8_WAIT_V(8); PG8_WAIT_L(0); PG8_BAR; PG8_MMA(1, 0, At, B0); PG8_MMA(1, 1, At, B1); PG8_BAR; PG8_SCHED;
;         }
	s_setprio 0
	s_add_i32 s93, 0, 0x18000
	s_add_i32 s94, 0, 0x1c000
	v_add_u32_e32 v174, s93, v148
	v_add_u32_e32 v190, s94, v148
	ds_read_b128 v[158:161], v174
	ds_read_b128 v[162:165], v174 offset:1024
	ds_read_b128 v[166:169], v174 offset:2048
	ds_read_b128 v[174:177], v174 offset:3072
	ds_read_b128 v[178:181], v190
	ds_read_b128 v[182:185], v190 offset:1024
	ds_read_b128 v[186:189], v190 offset:2048
	ds_read_b128 v[190:193], v190 offset:3072
	s_add_u32 s68, s68, 0x40000
	s_addc_u32 s69, s69, 0
	s_mov_b32 m0, s77
	ds_read_b128 v[194:197], v152 offset:32768
	ds_read_b128 v[198:201], v152 offset:33792
	ds_read_b128 v[202:205], v152 offset:34816
	ds_read_b128 v[206:209], v152 offset:35840
	ds_read_b128 v[210:213], v152 offset:36864
	ds_read_b128 v[214:217], v152 offset:37888
	ds_read_b128 v[218:221], v152 offset:38912
	ds_read_b128 v[222:225], v152 offset:39936
	global_load_lds_dwordx4 v130, s[68:69]
	s_mov_b32 m0, s78
	s_nop 0
	global_load_lds_dwordx4 v134, s[68:69]
	s_waitcnt vmcnt(8)
	s_waitcnt lgkmcnt(0)
	s_setprio 1
	s_barrier
	v_mfma_f32_16x16x32_bf16 v[126:129], v[158:161], v[194:197], v[126:129]
	v_mfma_f32_16x16x32_bf16 v[118:121], v[166:169], v[194:197], v[118:121]
	v_mfma_f32_16x16x32_bf16 v[110:113], v[158:161], v[202:205], v[110:113]
	v_mfma_f32_16x16x32_bf16 v[102:105], v[166:169], v[202:205], v[102:105]
	v_mfma_f32_16x16x32_bf16 v[94:97], v[158:161], v[210:213], v[94:97]
	v_mfma_f32_16x16x32_bf16 v[86:89], v[166:169], v[210:213], v[86:89]
	v_mfma_f32_16x16x32_bf16 v[78:81], v[158:161], v[218:221], v[78:81]
	v_mfma_f32_16x16x32_bf16 v[70:73], v[166:169], v[218:221], v[70:73]
	v_mfma_f32_16x16x32_bf16 v[126:129], v[162:165], v[198:201], v[126:129]
	v_mfma_f32_16x16x32_bf16 v[118:121], v[174:177], v[198:201], v[118:121]
	v_mfma_f32_16x16x32_bf16 v[110:113], v[162:165], v[206:209], v[110:113]
	v_mfma_f32_16x16x32_bf16 v[102:105], v[174:177], v[206:209], v[102:105]
	v_mfma_f32_16x16x32_bf16 v[94:97], v[162:165], v[214:217], v[94:97]
	v_mfma_f32_16x16x32_bf16 v[86:89], v[174:177], v[214:217], v[86:89]
	v_mfma_f32_16x16x32_bf16 v[78:81], v[162:165], v[222:225], v[78:81]
	v_mfma_f32_16x16x32_bf16 v[70:73], v[174:177], v[222:225], v[70:73]
	v_mfma_f32_16x16x32_bf16 v[122:125], v[178:181], v[194:197], v[122:125]
	v_mfma_f32_16x16x32_bf16 v[114:117], v[186:189], v[194:197], v[114:117]
	v_mfma_f32_16x16x32_bf16 v[106:109], v[178:181], v[202:205], v[106:109]
	v_mfma_f32_16x16x32_bf16 v[98:101], v[186:189], v[202:205], v[98:101]
	v_mfma_f32_16x16x32_bf16 v[90:93], v[178:181], v[210:213], v[90:93]
	v_mfma_f32_16x16x32_bf16 v[82:85], v[186:189], v[210:213], v[82:85]
	v_mfma_f32_16x16x32_bf16 v[74:77], v[178:181], v[218:221], v[74:77]
	v_mfma_f32_16x16x32_bf16 v[66:69], v[186:189], v[218:221], v[66:69]
	v_mfma_f32_16x16x32_bf16 v[122:125], v[182:185], v[198:201], v[122:125]
	v_mfma_f32_16x16x32_bf16 v[114:117], v[190:193], v[198:201], v[114:117]
	v_mfma_f32_16x16x32_bf16 v[106:109], v[182:185], v[206:209], v[106:109]
	v_mfma_f32_16x16x32_bf16 v[98:101], v[190:193], v[206:209], v[98:101]
	v_mfma_f32_16x16x32_bf16 v[90:93], v[182:185], v[214:217], v[90:93]
	v_mfma_f32_16x16x32_bf16 v[82:85], v[190:193], v[214:217], v[82:85]
	v_mfma_f32_16x16x32_bf16 v[74:77], v[182:185], v[222:225], v[74:77]
	v_mfma_f32_16x16x32_bf16 v[66:69], v[190:193], v[222:225], v[66:69]
	s_barrier
	s_setprio 0
	s_add_i32 s68, s93, s6
	s_mov_b32 m0, s68
	ds_read_b128 v[194:197], v152 offset:49152
	ds_read_b128 v[198:201], v152 offset:50176
	ds_read_b128 v[202:205], v152 offset:51200
	ds_read_b128 v[206:209], v152 offset:52224
	ds_read_b128 v[210:213], v152 offset:53248
	ds_read_b128 v[214:217], v152 offset:54272
	ds_read_b128 v[218:221], v152 offset:55296
	ds_read_b128 v[222:225], v152 offset:56320
	global_load_lds_dwordx4 v132, s[98:99]
	s_add_i32 m0, s68, 0x2000
	s_add_u32 s66, s66, 0x40080
	s_addc_u32 s67, s67, 0
	s_add_i32 s68, s94, s6
	global_load_lds_dwordx4 v136, s[98:99]
	s_mov_b32 m0, s68
	s_nop 0
	global_load_lds_dwordx4 v132, s[66:67]
	s_add_i32 m0, s68, 0x2000
	s_nop 0
	global_load_lds_dwordx4 v136, s[66:67]
	s_mov_b32 m0, s79
	s_nop 0
	global_load_lds_dwordx4 v130, s[100:101]
	s_mov_b32 m0, s80
	s_nop 0
	global_load_lds_dwordx4 v134, s[100:101]
	s_waitcnt vmcnt(8)
	s_waitcnt lgkmcnt(0)
	s_setprio 1
	s_barrier
	v_mfma_f32_16x16x32_bf16 v[62:65], v[158:161], v[194:197], v[62:65]
	v_mfma_f32_16x16x32_bf16 v[54:57], v[166:169], v[194:197], v[54:57]
	v_mfma_f32_16x16x32_bf16 v[46:49], v[158:161], v[202:205], v[46:49]
	v_mfma_f32_16x16x32_bf16 v[38:41], v[166:169], v[202:205], v[38:41]
	v_mfma_f32_16x16x32_bf16 v[30:33], v[158:161], v[210:213], v[30:33]
	v_mfma_f32_16x16x32_bf16 v[22:25], v[166:169], v[210:213], v[22:25]
	v_mfma_f32_16x16x32_bf16 v[14:17], v[158:161], v[218:221], v[14:17]
	v_mfma_f32_16x16x32_bf16 v[6:9], v[166:169], v[218:221], v[6:9]
	v_mfma_f32_16x16x32_bf16 v[62:65], v[162:165], v[198:201], v[62:65]
	v_mfma_f32_16x16x32_bf16 v[54:57], v[174:177], v[198:201], v[54:57]
	v_mfma_f32_16x16x32_bf16 v[46:49], v[162:165], v[206:209], v[46:49]
	v_mfma_f32_16x16x32_bf16 v[38:41], v[174:177], v[206:209], v[38:41]
	v_mfma_f32_16x16x32_bf16 v[30:33], v[162:165], v[214:217], v[30:33]
	v_mfma_f32_16x16x32_bf16 v[22:25], v[174:177], v[214:217], v[22:25]
	v_mfma_f32_16x16x32_bf16 v[14:17], v[162:165], v[222:225], v[14:17]
	v_mfma_f32_16x16x32_bf16 v[6:9], v[174:177], v[222:225], v[6:9]
	v_mfma_f32_16x16x32_bf16 v[58:61], v[178:181], v[194:197], v[58:61]
	v_mfma_f32_16x16x32_bf16 v[50:53], v[186:189], v[194:197], v[50:53]
	v_mfma_f32_16x16x32_bf16 v[42:45], v[178:181], v[202:205], v[42:45]
	v_mfma_f32_16x16x32_bf16 v[34:37], v[186:189], v[202:205], v[34:37]
	v_mfma_f32_16x16x32_bf16 v[26:29], v[178:181], v[210:213], v[26:29]
	v_mfma_f32_16x16x32_bf16 v[18:21], v[186:189], v[210:213], v[18:21]
	v_mfma_f32_16x16x32_bf16 v[10:13], v[178:181], v[218:221], v[10:13]
	v_mfma_f32_16x16x32_bf16 v[2:5], v[186:189], v[218:221], v[2:5]
	v_mfma_f32_16x16x32_bf16 v[58:61], v[182:185], v[198:201], v[58:61]
	v_mfma_f32_16x16x32_bf16 v[50:53], v[190:193], v[198:201], v[50:53]
	v_mfma_f32_16x16x32_bf16 v[42:45], v[182:185], v[206:209], v[42:45]
	v_mfma_f32_16x16x32_bf16 v[34:37], v[190:193], v[206:209], v[34:37]
	v_mfma_f32_16x16x32_bf16 v[26:29], v[182:185], v[214:217], v[26:29]
	v_mfma_f32_16x16x32_bf16 v[18:21], v[190:193], v[214:217], v[18:21]
	v_mfma_f32_16x16x32_bf16 v[10:13], v[182:185], v[222:225], v[10:13]
	v_mfma_f32_16x16x32_bf16 v[2:5], v[190:193], v[222:225], v[2:5]
	s_barrier
	s_setprio 0
	s_add_i32 s92, s92, 2
	s_add_u32 s64, s64, 0x100
	s_addc_u32 s65, s65, 0
	s_add_u32 s90, s90, 0x100
	s_addc_u32 s91, s91, 0
	s_cmp_gt_u32 s92, 13
	s_cbranch_scc0 .LBB0_134
	s_and_b64 vcc, exec, s[38:39]
	s_cbranch_vccz .LBB0_137
	s_barrier

; #define PG8_STAGE(bufoff, gbase, voff) do { _Pragma("unroll") for (int _i = 0; _i < 2; ++_i) \
;         __builtin_amdgcn_global_load_lds((const unsigned*)((const char*)(gbase) + (voff)[_i]), (LAS unsigned*)(lds + (bufoff) + ldsw + _i * 8192), 16, 0, 0); } while (0)
; #define PG8_LDA(dst, b, h) do { _Pragma("unroll") for (int m = 0; m < 4; ++m) _Pragma("unroll") for (int k = 0; k < 2; ++k) dst[m][k] = *(const LAS bf16x8*)(lds + PG8_SA(b, h) + aoff + m * 2048 + k * 1024); } while (0)
; #define PG8_LDB(dst, b, h) do { _Pragma("unroll") for (int n = 0; n < 2; ++n) _Pragma("unroll") for (int k = 0; k < 2; ++k) dst[n][k] = *(const LAS bf16x8*)(lds + PG8_SB(b, h) + boff + n * 2048 + k * 1024); } while (0)
; #define PG8_MMA(ai, bj, At, Bt) do { __builtin_amdgcn_s_setprio(1); _Pragma("unroll") for (int m = 0; m < 4; ++m) _Pragma("unroll") for (int n = 0; n < 2; ++n) _Pragma("unroll") for (int k = 0; k < 2; ++k) \
;         acc[ai][bj][m][n] = __builtin_amdgcn_mfma_f32_16x16x32_bf16(Bt[n][k], At[m][k], acc[ai][bj][m][n], 0, 0, 0); __builtin_amdgcn_s_setprio(0); } while (0)
; #define PG8_WAIT_V(n) asm volatile("s_waitcnt vmcnt(" #n ")" ::: "memory")
; #define PG8_WAIT_L(n) asm volatile("s_waitcnt lgkmcnt(" #n ")" ::: "memory")
; #define PG8_BAR __builtin_amdgcn_s_barrier()
; template <class Epi>
; __device__ __forceinline__ void gemm_phase(LAS unsigned char* lds, const Gemm g, const StaticOrder& S, const Epi& E) {
;     ...
;             const bool last = (t == nt - 2);
;             const char* a1 = cA + (size_t)(t + 1) * kstep;
;             const char* a2 = last ? nA : cA + (size_t)(t + 2) * kstep; const char* b2 = last ? nB : cB + (size_t)(t + 2) * kstep;
;             const char* a3 = a2 + kstep; const char* b3 = b2 + kstep;
;             if constexpr (Epi::MIDK > 0) { if (t == Epi::MIDK) E.mid(acc, cur, wr, wc, fr, fq); }
;             PG8_LDB(B0, 0, 0); PG8_LDB(B1, 0, 1); PG8_SCHED; PG8_LDA(At, 0, 0); PG8_STAGE(PG8_SA(1, 1), a1 + hstep, voffA);
;             PG8_WAIT_V(8); PG8_WAIT_L(0); PG8_BAR; PG8_MMA(0, 0, At, B0); PG8_MMA(0, 1, At, B1); PG8_BAR; PG8_SCHED;
;             PG8_LDA(At, 0, 1); PG8_STAGE(PG8_SB(0, 0), b2, voffB); PG8_STAGE(PG8_SB(0, 1), b2 + hstep, voffB); PG8_STAGE(PG8_SA(0, 0), a2, voffA);
;             PG8_WAIT_V(8); PG8_WAIT_L(0); PG8_BAR; PG8_MMA(1, 0, At, B0); PG8_MMA(1, 1, At, B1); PG8_BAR; PG8_SCHED;
.LBB0_221:
	ds_read_b128 v[130:133], v162
	ds_read_b128 v[134:137], v162 offset:1024
	ds_read_b128 v[154:157], v162 offset:2048
	ds_read_b128 v[166:169], v162 offset:3072
	ds_read_b128 v[174:177], v163
	ds_read_b128 v[178:181], v163 offset:1024
	ds_read_b128 v[182:185], v163 offset:2048
	ds_read_b128 v[186:189], v163 offset:3072
	s_add_u32 s48, s46, 0xfff50080
	s_addc_u32 s49, s47, -1
	s_cmp_eq_u32 s84, 40
	s_cselect_b32 s51, s5, s49
	s_cselect_b32 s50, s4, s48
	s_cselect_b32 s49, s45, s83
	s_cselect_b32 s48, s44, s82
	s_add_i32 m0, s59, 0xc000
	ds_read_b128 v[190:193], v164
	ds_read_b128 v[194:197], v164 offset:1024
	ds_read_b128 v[198:201], v164 offset:2048
	ds_read_b128 v[202:205], v164 offset:3072
	ds_read_b128 v[206:209], v164 offset:4096
	ds_read_b128 v[210:213], v164 offset:5120
	ds_read_b128 v[214:217], v164 offset:6144
	ds_read_b128 v[218:221], v164 offset:7168
	global_load_lds_dwordx4 v146, s[46:47]
	s_add_i32 m0, s59, 0xe000
	s_nop 0
	global_load_lds_dwordx4 v148, s[46:47]
	s_waitcnt vmcnt(8)
	s_waitcnt lgkmcnt(0)
	s_setprio 1
	s_barrier
	v_mfma_f32_16x16x32_bf16 v[126:129], v[130:133], v[190:193], v[126:129]
	v_mfma_f32_16x16x32_bf16 v[122:125], v[154:157], v[190:193], v[122:125]
	v_mfma_f32_16x16x32_bf16 v[110:113], v[130:133], v[198:201], v[110:113]
	v_mfma_f32_16x16x32_bf16 v[106:109], v[154:157], v[198:201], v[106:109]
	v_mfma_f32_16x16x32_bf16 v[94:97], v[130:133], v[206:209], v[94:97]
	v_mfma_f32_16x16x32_bf16 v[90:93], v[154:157], v[206:209], v[90:93]
	v_mfma_f32_16x16x32_bf16 v[78:81], v[130:133], v[214:217], v[78:81]
	v_mfma_f32_16x16x32_bf16 v[74:77], v[154:157], v[214:217], v[74:77]
	v_mfma_f32_16x16x32_bf16 v[126:129], v[134:137], v[194:197], v[126:129]
	v_mfma_f32_16x16x32_bf16 v[122:125], v[166:169], v[194:197], v[122:125]
	v_mfma_f32_16x16x32_bf16 v[110:113], v[134:137], v[202:205], v[110:113]
	v_mfma_f32_16x16x32_bf16 v[106:109], v[166:169], v[202:205], v[106:109]
	v_mfma_f32_16x16x32_bf16 v[94:97], v[134:137], v[210:213], v[94:97]
	v_mfma_f32_16x16x32_bf16 v[90:93], v[166:169], v[210:213], v[90:93]
	v_mfma_f32_16x16x32_bf16 v[78:81], v[134:137], v[218:221], v[78:81]
	v_mfma_f32_16x16x32_bf16 v[74:77], v[166:169], v[218:221], v[74:77]
	v_mfma_f32_16x16x32_bf16 v[118:121], v[174:177], v[190:193], v[118:121]
	v_mfma_f32_16x16x32_bf16 v[114:117], v[182:185], v[190:193], v[114:117]
	v_mfma_f32_16x16x32_bf16 v[102:105], v[174:177], v[198:201], v[102:105]
	v_mfma_f32_16x16x32_bf16 v[98:101], v[182:185], v[198:201], v[98:101]
	v_mfma_f32_16x16x32_bf16 v[86:89], v[174:177], v[206:209], v[86:89]
	v_mfma_f32_16x16x32_bf16 v[82:85], v[182:185], v[206:209], v[82:85]
	v_mfma_f32_16x16x32_bf16 v[70:73], v[174:177], v[214:217], v[70:73]
	v_mfma_f32_16x16x32_bf16 v[66:69], v[182:185], v[214:217], v[66:69]
	v_mfma_f32_16x16x32_bf16 v[118:121], v[178:181], v[194:197], v[118:121]
	v_mfma_f32_16x16x32_bf16 v[114:117], v[186:189], v[194:197], v[114:117]
	v_mfma_f32_16x16x32_bf16 v[102:105], v[178:181], v[202:205], v[102:105]
	v_mfma_f32_16x16x32_bf16 v[98:101], v[186:189], v[202:205], v[98:101]
	v_mfma_f32_16x16x32_bf16 v[86:89], v[178:181], v[210:213], v[86:89]
	v_mfma_f32_16x16x32_bf16 v[82:85], v[186:189], v[210:213], v[82:85]
	v_mfma_f32_16x16x32_bf16 v[70:73], v[178:181], v[218:221], v[70:73]
	v_mfma_f32_16x16x32_bf16 v[66:69], v[186:189], v[218:221], v[66:69]
	s_barrier
	s_setprio 0
	s_add_u32 s98, s48, s38
	s_addc_u32 s99, s49, s39
	s_add_u32 s100, s50, s38
	s_addc_u32 s101, s51, s39
	s_add_i32 s85, s76, s58
	s_mov_b32 m0, s85
	ds_read_b128 v[190:193], v164 offset:16384
	ds_read_b128 v[194:197], v164 offset:17408
	ds_read_b128 v[198:201], v164 offset:18432
	ds_read_b128 v[202:205], v164 offset:19456
	ds_read_b128 v[206:209], v164 offset:20480
	ds_read_b128 v[210:213], v164 offset:21504
	ds_read_b128 v[214:217], v164 offset:22528
	ds_read_b128 v[218:221], v164 offset:23552
	global_load_lds_dwordx4 v140, s[48:49]
	s_add_i32 m0, s85, 0x2000
	s_add_u32 s86, s48, 0xb0000
	s_addc_u32 s87, s49, 0
	s_add_i32 s85, s77, s58
	global_load_lds_dwordx4 v144, s[48:49]
	s_mov_b32 m0, s85
	s_nop 0
	global_load_lds_dwordx4 v140, s[86:87]
	s_add_i32 m0, s85, 0x2000
	s_nop 0
	global_load_lds_dwordx4 v144, s[86:87]
	s_mov_b32 m0, s59
	s_nop 0
	global_load_lds_dwordx4 v138, s[50:51]
	s_mov_b32 m0, s60
	s_nop 0
	global_load_lds_dwordx4 v142, s[50:51]
	s_waitcnt vmcnt(8)
	s_waitcnt lgkmcnt(0)
	s_setprio 1
	s_barrier
	v_mfma_f32_16x16x32_bf16 v[62:65], v[130:133], v[190:193], v[62:65]
	v_mfma_f32_16x16x32_bf16 v[58:61], v[154:157], v[190:193], v[58:61]
	v_mfma_f32_16x16x32_bf16 v[46:49], v[130:133], v[198:201], v[46:49]
	v_mfma_f32_16x16x32_bf16 v[42:45], v[154:157], v[198:201], v[42:45]
	v_mfma_f32_16x16x32_bf16 v[30:33], v[130:133], v[206:209], v[30:33]
	v_mfma_f32_16x16x32_bf16 v[26:29], v[154:157], v[206:209], v[26:29]
	v_mfma_f32_16x16x32_bf16 v[14:17], v[130:133], v[214:217], v[14:17]
	v_mfma_f32_16x16x32_bf16 v[10:13], v[154:157], v[214:217], v[10:13]
	v_mfma_f32_16x16x32_bf16 v[62:65], v[134:137], v[194:197], v[62:65]
	v_mfma_f32_16x16x32_bf16 v[58:61], v[166:169], v[194:197], v[58:61]
	v_mfma_f32_16x16x32_bf16 v[46:49], v[134:137], v[202:205], v[46:49]
	v_mfma_f32_16x16x32_bf16 v[42:45], v[166:169], v[202:205], v[42:45]
	v_mfma_f32_16x16x32_bf16 v[30:33], v[134:137], v[210:213], v[30:33]
	v_mfma_f32_16x16x32_bf16 v[26:29], v[166:169], v[210:213], v[26:29]
	v_mfma_f32_16x16x32_bf16 v[14:17], v[134:137], v[218:221], v[14:17]
	v_mfma_f32_16x16x32_bf16 v[10:13], v[166:169], v[218:221], v[10:13]
	v_mfma_f32_16x16x32_bf16 v[54:57], v[174:177], v[190:193], v[54:57]
	v_mfma_f32_16x16x32_bf16 v[50:53], v[182:185], v[190:193], v[50:53]
	v_mfma_f32_16x16x32_bf16 v[38:41], v[174:177], v[198:201], v[38:41]
	v_mfma_f32_16x16x32_bf16 v[34:37], v[182:185], v[198:201], v[34:37]
	v_mfma_f32_16x16x32_bf16 v[22:25], v[174:177], v[206:209], v[22:25]
	v_mfma_f32_16x16x32_bf16 v[18:21], v[182:185], v[206:209], v[18:21]
	v_mfma_f32_16x16x32_bf16 v[6:9], v[174:177], v[214:217], v[6:9]
	v_mfma_f32_16x16x32_bf16 v[2:5], v[182:185], v[214:217], v[2:5]
	v_mfma_f32_16x16x32_bf16 v[54:57], v[178:181], v[194:197], v[54:57]
	v_mfma_f32_16x16x32_bf16 v[50:53], v[186:189], v[194:197], v[50:53]
	v_mfma_f32_16x16x32_bf16 v[38:41], v[178:181], v[202:205], v[38:41]
	v_mfma_f32_16x16x32_bf16 v[34:37], v[186:189], v[202:205], v[34:37]
	v_mfma_f32_16x16x32_bf16 v[22:25], v[178:181], v[210:213], v[22:25]
	v_mfma_f32_16x16x32_bf16 v[18:21], v[186:189], v[210:213], v[18:21]
	v_mfma_f32_16x16x32_bf16 v[6:9], v[178:181], v[218:221], v[6:9]
	v_mfma_f32_16x16x32_bf16 v[2:5], v[186:189], v[218:221], v[2:5]
	s_barrier
; #define PG8_STAGE(bufoff, gbase, voff) do { _Pragma("unroll") for (int _i = 0; _i < 2; ++_i) \
;         __builtin_amdgcn_global_load_lds((const unsigned*)((const char*)(gbase) + (voff)[_i]), (LAS unsigned*)(lds + (bufoff) + ldsw + _i * 8192), 16, 0, 0); } while (0)
; #define PG8_LDA(dst, b, h) do { _Pragma("unroll") for (int m = 0; m < 4; ++m) _Pragma("unroll") for (int k = 0; k < 2; ++k) dst[m][k] = *(const LAS bf16x8*)(lds + PG8_SA(b, h) + aoff + m * 2048 + k * 1024); } while (0)
; #define PG8_LDB(dst, b, h) do { _Pragma("unroll") for (int n = 0; n < 2; ++n) _Pragma("unroll") for (int k = 0; k < 2; ++k) dst[n][k] = *(const LAS bf16x8*)(lds + PG8_SB(b, h) + boff + n * 2048 + k * 1024); } while (0)
; #define PG8_MMA(ai, bj, At, Bt) do { __builtin_amdgcn_s_setprio(1); _Pragma("unroll") for (int m = 0; m < 4; ++m) _Pragma("unroll") for (int n = 0; n < 2; ++n) _Pragma("unroll") for (int k = 0; k < 2; ++k) \
;         acc[ai][bj][m][n] = __builtin_amdgcn_mfma_f32_16x16x32_bf16(Bt[n][k], At[m][k], acc[ai][bj][m][n], 0, 0, 0); __builtin_amdgcn_s_setprio(0); } while (0)
; #define PG8_WAIT_V(n) asm volatile("s_waitcnt vmcnt(" #n ")" ::: "memory")
; #define PG8_WAIT_L(n) asm volatile("s_waitcnt lgkmcnt(" #n ")" ::: "memory")
; #define PG8_BAR __builtin_amdgcn_s_barrier()
; #define PG8_SCHED __builtin_amdgcn_sched_barrier(0)
; template <class Epi>
; __device__ __forceinline__ void gemm_phase(LAS unsigned char* lds, const Gemm g, const StaticOrder& S, const Epi& E) {
;     ...
;             PG8_LDB(B0, 1, 0); PG8_LDB(B1, 1, 1); PG8_SCHED; PG8_LDA(At, 1, 0); PG8_STAGE(PG8_SA(0, 1), a2 + hstep, voffA);
;             PG8_WAIT_V(8); PG8_WAIT_L(0); PG8_BAR; PG8_MMA(0, 0, At, B0); PG8_MMA(0, 1, At, B1); PG8_BAR; PG8_SCHED;
;             PG8_LDA(At, 1, 1); PG8_STAGE(PG8_SB(1, 0), b3, voffB); PG8_STAGE(PG8_SB(1, 1), b3 + hstep, voffB); PG8_STAGE(PG8_SA(1, 0), a3, voffA);
;             PG8_WAIT_V(8); PG8_WAIT_L(0); PG8_BAR; PG8_MMA(1, 0, At, B0); PG8_MMA(1, 1, At, B1); PG8_BAR; PG8_SCHED;
;         }
;         if (wr == 0) PG8_BAR;
	s_setprio 0
	s_add_i32 s85, 0, 0x18000
	s_add_i32 s86, 0, 0x1c000
	v_add_u32_e32 v166, s85, v160
	v_add_u32_e32 v186, s86, v160
	ds_read_b128 v[130:133], v166
	ds_read_b128 v[134:137], v166 offset:1024
	ds_read_b128 v[154:157], v166 offset:2048
	ds_read_b128 v[166:169], v166 offset:3072
	ds_read_b128 v[174:177], v186
	ds_read_b128 v[178:181], v186 offset:1024
	ds_read_b128 v[182:185], v186 offset:2048
	ds_read_b128 v[186:189], v186 offset:3072
	s_add_u32 s50, s50, 0xb0000
	s_addc_u32 s51, s51, 0
	s_mov_b32 m0, s61
	ds_read_b128 v[190:193], v164 offset:32768
	ds_read_b128 v[194:197], v164 offset:33792
	ds_read_b128 v[198:201], v164 offset:34816
	ds_read_b128 v[202:205], v164 offset:35840
	ds_read_b128 v[206:209], v164 offset:36864
	ds_read_b128 v[210:213], v164 offset:37888
	ds_read_b128 v[214:217], v164 offset:38912
	ds_read_b128 v[218:221], v164 offset:39936
	global_load_lds_dwordx4 v138, s[50:51]
	s_mov_b32 m0, s62
	s_nop 0
	global_load_lds_dwordx4 v142, s[50:51]
	s_waitcnt vmcnt(8)
	s_waitcnt lgkmcnt(0)
	s_setprio 1
	s_barrier
	v_mfma_f32_16x16x32_bf16 v[126:129], v[130:133], v[190:193], v[126:129]
	v_mfma_f32_16x16x32_bf16 v[122:125], v[154:157], v[190:193], v[122:125]
	v_mfma_f32_16x16x32_bf16 v[110:113], v[130:133], v[198:201], v[110:113]
	v_mfma_f32_16x16x32_bf16 v[106:109], v[154:157], v[198:201], v[106:109]
	v_mfma_f32_16x16x32_bf16 v[94:97], v[130:133], v[206:209], v[94:97]
	v_mfma_f32_16x16x32_bf16 v[90:93], v[154:157], v[206:209], v[90:93]
	v_mfma_f32_16x16x32_bf16 v[78:81], v[130:133], v[214:217], v[78:81]
	v_mfma_f32_16x16x32_bf16 v[74:77], v[154:157], v[214:217], v[74:77]
	v_mfma_f32_16x16x32_bf16 v[126:129], v[134:137], v[194:197], v[126:129]
	v_mfma_f32_16x16x32_bf16 v[122:125], v[166:169], v[194:197], v[122:125]
	v_mfma_f32_16x16x32_bf16 v[110:113], v[134:137], v[202:205], v[110:113]
	v_mfma_f32_16x16x32_bf16 v[106:109], v[166:169], v[202:205], v[106:109]
	v_mfma_f32_16x16x32_bf16 v[94:97], v[134:137], v[210:213], v[94:97]
	v_mfma_f32_16x16x32_bf16 v[90:93], v[166:169], v[210:213], v[90:93]
	v_mfma_f32_16x16x32_bf16 v[78:81], v[134:137], v[218:221], v[78:81]
	v_mfma_f32_16x16x32_bf16 v[74:77], v[166:169], v[218:221], v[74:77]
	v_mfma_f32_16x16x32_bf16 v[118:121], v[174:177], v[190:193], v[118:121]
	v_mfma_f32_16x16x32_bf16 v[114:117], v[182:185], v[190:193], v[114:117]
	v_mfma_f32_16x16x32_bf16 v[102:105], v[174:177], v[198:201], v[102:105]
	v_mfma_f32_16x16x32_bf16 v[98:101], v[182:185], v[198:201], v[98:101]
	v_mfma_f32_16x16x32_bf16 v[86:89], v[174:177], v[206:209], v[86:89]
	v_mfma_f32_16x16x32_bf16 v[82:85], v[182:185], v[206:209], v[82:85]
	v_mfma_f32_16x16x32_bf16 v[70:73], v[174:177], v[214:217], v[70:73]
	v_mfma_f32_16x16x32_bf16 v[66:69], v[182:185], v[214:217], v[66:69]
	v_mfma_f32_16x16x32_bf16 v[118:121], v[178:181], v[194:197], v[118:121]
	v_mfma_f32_16x16x32_bf16 v[114:117], v[186:189], v[194:197], v[114:117]
	v_mfma_f32_16x16x32_bf16 v[102:105], v[178:181], v[202:205], v[102:105]
	v_mfma_f32_16x16x32_bf16 v[98:101], v[186:189], v[202:205], v[98:101]
	v_mfma_f32_16x16x32_bf16 v[86:89], v[178:181], v[210:213], v[86:89]
	v_mfma_f32_16x16x32_bf16 v[82:85], v[186:189], v[210:213], v[82:85]
	v_mfma_f32_16x16x32_bf16 v[70:73], v[178:181], v[218:221], v[70:73]
	v_mfma_f32_16x16x32_bf16 v[66:69], v[186:189], v[218:221], v[66:69]
	s_barrier
	s_setprio 0
	s_add_i32 s50, s85, s58
	s_mov_b32 m0, s50
	ds_read_b128 v[190:193], v164 offset:49152
	ds_read_b128 v[194:197], v164 offset:50176
	ds_read_b128 v[198:201], v164 offset:51200
	ds_read_b128 v[202:205], v164 offset:52224
	ds_read_b128 v[206:209], v164 offset:53248
	ds_read_b128 v[210:213], v164 offset:54272
	ds_read_b128 v[214:217], v164 offset:55296
	ds_read_b128 v[218:221], v164 offset:56320
	global_load_lds_dwordx4 v140, s[98:99]
	s_add_i32 m0, s50, 0x2000
	s_add_u32 s48, s48, 0xb0080
	s_addc_u32 s49, s49, 0
	s_add_i32 s50, s86, s58
	global_load_lds_dwordx4 v144, s[98:99]
	s_mov_b32 m0, s50
	s_nop 0
	global_load_lds_dwordx4 v140, s[48:49]
	s_add_i32 m0, s50, 0x2000
	s_nop 0
	global_load_lds_dwordx4 v144, s[48:49]
	s_mov_b32 m0, s64
	s_nop 0
	global_load_lds_dwordx4 v138, s[100:101]
	s_mov_b32 m0, s65
	s_nop 0
	global_load_lds_dwordx4 v142, s[100:101]
	s_waitcnt vmcnt(8)
	s_waitcnt lgkmcnt(0)
	s_setprio 1
	s_barrier
	v_mfma_f32_16x16x32_bf16 v[62:65], v[130:133], v[190:193], v[62:65]
	v_mfma_f32_16x16x32_bf16 v[58:61], v[154:157], v[190:193], v[58:61]
	v_mfma_f32_16x16x32_bf16 v[46:49], v[130:133], v[198:201], v[46:49]
	v_mfma_f32_16x16x32_bf16 v[42:45], v[154:157], v[198:201], v[42:45]
	v_mfma_f32_16x16x32_bf16 v[30:33], v[130:133], v[206:209], v[30:33]
	v_mfma_f32_16x16x32_bf16 v[26:29], v[154:157], v[206:209], v[26:29]
	v_mfma_f32_16x16x32_bf16 v[14:17], v[130:133], v[214:217], v[14:17]
	v_mfma_f32_16x16x32_bf16 v[10:13], v[154:157], v[214:217], v[10:13]
	v_mfma_f32_16x16x32_bf16 v[62:65], v[134:137], v[194:197], v[62:65]
	v_mfma_f32_16x16x32_bf16 v[58:61], v[166:169], v[194:197], v[58:61]
	v_mfma_f32_16x16x32_bf16 v[46:49], v[134:137], v[202:205], v[46:49]
	v_mfma_f32_16x16x32_bf16 v[42:45], v[166:169], v[202:205], v[42:45]
	v_mfma_f32_16x16x32_bf16 v[30:33], v[134:137], v[210:213], v[30:33]
	v_mfma_f32_16x16x32_bf16 v[26:29], v[166:169], v[210:213], v[26:29]
	v_mfma_f32_16x16x32_bf16 v[14:17], v[134:137], v[218:221], v[14:17]
	v_mfma_f32_16x16x32_bf16 v[10:13], v[166:169], v[218:221], v[10:13]
	v_mfma_f32_16x16x32_bf16 v[54:57], v[174:177], v[190:193], v[54:57]
	v_mfma_f32_16x16x32_bf16 v[50:53], v[182:185], v[190:193], v[50:53]
	v_mfma_f32_16x16x32_bf16 v[38:41], v[174:177], v[198:201], v[38:41]
	v_mfma_f32_16x16x32_bf16 v[34:37], v[182:185], v[198:201], v[34:37]
	v_mfma_f32_16x16x32_bf16 v[22:25], v[174:177], v[206:209], v[22:25]
	v_mfma_f32_16x16x32_bf16 v[18:21], v[182:185], v[206:209], v[18:21]
	v_mfma_f32_16x16x32_bf16 v[6:9], v[174:177], v[214:217], v[6:9]
	v_mfma_f32_16x16x32_bf16 v[2:5], v[182:185], v[214:217], v[2:5]
	v_mfma_f32_16x16x32_bf16 v[54:57], v[178:181], v[194:197], v[54:57]
	v_mfma_f32_16x16x32_bf16 v[50:53], v[186:189], v[194:197], v[50:53]
	v_mfma_f32_16x16x32_bf16 v[38:41], v[178:181], v[202:205], v[38:41]
	v_mfma_f32_16x16x32_bf16 v[34:37], v[186:189], v[202:205], v[34:37]
	v_mfma_f32_16x16x32_bf16 v[22:25], v[178:181], v[210:213], v[22:25]
	v_mfma_f32_16x16x32_bf16 v[18:21], v[186:189], v[210:213], v[18:21]
	v_mfma_f32_16x16x32_bf16 v[6:9], v[178:181], v[218:221], v[6:9]
	v_mfma_f32_16x16x32_bf16 v[2:5], v[186:189], v[218:221], v[2:5]
	s_barrier
	s_setprio 0
	s_add_i32 s84, s84, 2
	s_add_u32 s46, s46, 0x100
	s_addc_u32 s47, s47, 0
	s_add_u32 s82, s82, 0x100
	s_addc_u32 s83, s83, 0
	s_cmp_gt_u32 s84, 41
	s_cbranch_scc0 .LBB0_221
	s_and_b64 vcc, exec, s[42:43]
	s_cbranch_vccz .LBB0_224
	s_barrier

; #define PG8_STAGE(bufoff, gbase, voff) do { _Pragma("unroll") for (int _i = 0; _i < 2; ++_i) \
;         __builtin_amdgcn_global_load_lds((const unsigned*)((const char*)(gbase) + (voff)[_i]), (LAS unsigned*)(lds + (bufoff) + ldsw + _i * 8192), 16, 0, 0); } while (0)
; #define PG8_LDA(dst, b, h) do { _Pragma("unroll") for (int m = 0; m < 4; ++m) _Pragma("unroll") for (int k = 0; k < 2; ++k) dst[m][k] = *(const LAS bf16x8*)(lds + PG8_SA(b, h) + aoff + m * 2048 + k * 1024); } while (0)
; #define PG8_LDB(dst, b, h) do { _Pragma("unroll") for (int n = 0; n < 2; ++n) _Pragma("unroll") for (int k = 0; k < 2; ++k) dst[n][k] = *(const LAS bf16x8*)(lds + PG8_SB(b, h) + boff + n * 2048 + k * 1024); } while (0)
; #define PG8_MMA(ai, bj, At, Bt) do { __builtin_amdgcn_s_setprio(1); _Pragma("unroll") for (int m = 0; m < 4; ++m) _Pragma("unroll") for (int n = 0; n < 2; ++n) _Pragma("unroll") for (int k = 0; k < 2; ++k) \
;         acc[ai][bj][m][n] = __builtin_amdgcn_mfma_f32_16x16x32_bf16(Bt[n][k], At[m][k], acc[ai][bj][m][n], 0, 0, 0); __builtin_amdgcn_s_setprio(0); } while (0)
; #define PG8_WAIT_V(n) asm volatile("s_waitcnt vmcnt(" #n ")" ::: "memory")
; #define PG8_WAIT_L(n) asm volatile("s_waitcnt lgkmcnt(" #n ")" ::: "memory")
; #define PG8_BAR __builtin_amdgcn_s_barrier()
; template <class Epi>
; __device__ __forceinline__ void gemm_phase(LAS unsigned char* lds, const Gemm g, const StaticOrder& S, const Epi& E) {
;     ...
;             const bool last = (t == nt - 2);
;             const char* a1 = cA + (size_t)(t + 1) * kstep;
;             const char* a2 = last ? nA : cA + (size_t)(t + 2) * kstep; const char* b2 = last ? nB : cB + (size_t)(t + 2) * kstep;
;             const char* a3 = a2 + kstep; const char* b3 = b2 + kstep;
;             if constexpr (Epi::MIDK > 0) { if (t == Epi::MIDK) E.mid(acc, cur, wr, wc, fr, fq); }
;             PG8_LDB(B0, 0, 0); PG8_LDB(B1, 0, 1); PG8_SCHED; PG8_LDA(At, 0, 0); PG8_STAGE(PG8_SA(1, 1), a1 + hstep, voffA);
;             PG8_WAIT_V(8); PG8_WAIT_L(0); PG8_BAR; PG8_MMA(0, 0, At, B0); PG8_MMA(0, 1, At, B1); PG8_BAR; PG8_SCHED;
;             PG8_LDA(At, 0, 1); PG8_STAGE(PG8_SB(0, 0), b2, voffB); PG8_STAGE(PG8_SB(0, 1), b2 + hstep, voffB); PG8_STAGE(PG8_SA(0, 0), a2, voffA);
;             PG8_WAIT_V(8); PG8_WAIT_L(0); PG8_BAR; PG8_MMA(1, 0, At, B0); PG8_MMA(1, 1, At, B1); PG8_BAR; PG8_SCHED;
.LBB0_619:
	ds_read_b128 v[154:157], v174
	ds_read_b128 v[158:161], v174 offset:1024
	ds_read_b128 v[162:165], v174 offset:2048
	ds_read_b128 v[166:169], v174 offset:3072
	ds_read_b128 v[182:185], v175
	ds_read_b128 v[186:189], v175 offset:1024
	ds_read_b128 v[190:193], v175 offset:2048
	ds_read_b128 v[194:197], v175 offset:3072
	s_add_u32 s46, s44, 0xfffc0080
	s_addc_u32 s47, s45, -1
	s_cmp_eq_u32 s69, 12
	s_cselect_b32 s49, s64, s47
	s_cselect_b32 s48, s65, s46
	s_cselect_b32 s47, s25, s68
	s_cselect_b32 s46, s66, s67
	s_add_i32 m0, s43, 0xc000
	ds_read_b128 v[198:201], v176
	ds_read_b128 v[202:205], v176 offset:1024
	ds_read_b128 v[206:209], v176 offset:2048
	ds_read_b128 v[210:213], v176 offset:3072
	ds_read_b128 v[214:217], v176 offset:4096
	ds_read_b128 v[218:221], v176 offset:5120
	ds_read_b128 v[222:225], v176 offset:6144
	ds_read_b128 v[226:229], v176 offset:7168
	global_load_lds_dwordx4 v144, s[44:45]
	s_add_i32 m0, s43, 0xe000
	s_nop 0
	global_load_lds_dwordx4 v146, s[44:45]
	s_waitcnt vmcnt(8)
	s_waitcnt lgkmcnt(0)
	s_setprio 1
	s_barrier
	v_mfma_f32_16x16x32_bf16 v[126:129], v[154:157], v[198:201], v[126:129]
	v_mfma_f32_16x16x32_bf16 v[122:125], v[162:165], v[198:201], v[122:125]
	v_mfma_f32_16x16x32_bf16 v[110:113], v[154:157], v[206:209], v[110:113]
	v_mfma_f32_16x16x32_bf16 v[106:109], v[162:165], v[206:209], v[106:109]
	v_mfma_f32_16x16x32_bf16 v[94:97], v[154:157], v[214:217], v[94:97]
	v_mfma_f32_16x16x32_bf16 v[90:93], v[162:165], v[214:217], v[90:93]
	v_mfma_f32_16x16x32_bf16 v[78:81], v[154:157], v[222:225], v[78:81]
	v_mfma_f32_16x16x32_bf16 v[74:77], v[162:165], v[222:225], v[74:77]
	v_mfma_f32_16x16x32_bf16 v[126:129], v[158:161], v[202:205], v[126:129]
	v_mfma_f32_16x16x32_bf16 v[122:125], v[166:169], v[202:205], v[122:125]
	v_mfma_f32_16x16x32_bf16 v[110:113], v[158:161], v[210:213], v[110:113]
	v_mfma_f32_16x16x32_bf16 v[106:109], v[166:169], v[210:213], v[106:109]
	v_mfma_f32_16x16x32_bf16 v[94:97], v[158:161], v[218:221], v[94:97]
	v_mfma_f32_16x16x32_bf16 v[90:93], v[166:169], v[218:221], v[90:93]
	v_mfma_f32_16x16x32_bf16 v[78:81], v[158:161], v[226:229], v[78:81]
	v_mfma_f32_16x16x32_bf16 v[74:77], v[166:169], v[226:229], v[74:77]
	v_mfma_f32_16x16x32_bf16 v[118:121], v[182:185], v[198:201], v[118:121]
	v_mfma_f32_16x16x32_bf16 v[114:117], v[190:193], v[198:201], v[114:117]
	v_mfma_f32_16x16x32_bf16 v[102:105], v[182:185], v[206:209], v[102:105]
	v_mfma_f32_16x16x32_bf16 v[98:101], v[190:193], v[206:209], v[98:101]
	v_mfma_f32_16x16x32_bf16 v[86:89], v[182:185], v[214:217], v[86:89]
	v_mfma_f32_16x16x32_bf16 v[82:85], v[190:193], v[214:217], v[82:85]
	v_mfma_f32_16x16x32_bf16 v[70:73], v[182:185], v[222:225], v[70:73]
	v_mfma_f32_16x16x32_bf16 v[66:69], v[190:193], v[222:225], v[66:69]
	v_mfma_f32_16x16x32_bf16 v[118:121], v[186:189], v[202:205], v[118:121]
	v_mfma_f32_16x16x32_bf16 v[114:117], v[194:197], v[202:205], v[114:117]
	v_mfma_f32_16x16x32_bf16 v[102:105], v[186:189], v[210:213], v[102:105]
	v_mfma_f32_16x16x32_bf16 v[98:101], v[194:197], v[210:213], v[98:101]
	v_mfma_f32_16x16x32_bf16 v[86:89], v[186:189], v[218:221], v[86:89]
	v_mfma_f32_16x16x32_bf16 v[82:85], v[194:197], v[218:221], v[82:85]
	v_mfma_f32_16x16x32_bf16 v[70:73], v[186:189], v[226:229], v[70:73]
	v_mfma_f32_16x16x32_bf16 v[66:69], v[194:197], v[226:229], v[66:69]
	s_barrier
	s_setprio 0
	s_add_u32 s98, s46, s8
	s_addc_u32 s99, s47, s9
	s_add_u32 s100, s48, s8
	s_addc_u32 s101, s49, s9
	s_add_i32 s76, s60, s6
	s_mov_b32 m0, s76
	ds_read_b128 v[198:201], v176 offset:16384
	ds_read_b128 v[202:205], v176 offset:17408
	ds_read_b128 v[206:209], v176 offset:18432
	ds_read_b128 v[210:213], v176 offset:19456
	ds_read_b128 v[214:217], v176 offset:20480
	ds_read_b128 v[218:221], v176 offset:21504
	ds_read_b128 v[222:225], v176 offset:22528
	ds_read_b128 v[226:229], v176 offset:23552
	global_load_lds_dwordx4 v132, s[46:47]
	s_add_i32 m0, s76, 0x2000
	s_add_u32 s76, s46, 0x40000
	s_addc_u32 s77, s47, 0
	s_add_i32 s78, s61, s6
	global_load_lds_dwordx4 v136, s[46:47]
	s_mov_b32 m0, s78
	s_nop 0
	global_load_lds_dwordx4 v132, s[76:77]
	s_add_i32 m0, s78, 0x2000
	s_nop 0
	global_load_lds_dwordx4 v136, s[76:77]
	s_mov_b32 m0, s43
	s_nop 0
	global_load_lds_dwordx4 v130, s[48:49]
	s_mov_b32 m0, s51
	s_nop 0
	global_load_lds_dwordx4 v134, s[48:49]
	s_waitcnt vmcnt(8)
	s_waitcnt lgkmcnt(0)
	s_setprio 1
	s_barrier
	v_mfma_f32_16x16x32_bf16 v[62:65], v[154:157], v[198:201], v[62:65]
	v_mfma_f32_16x16x32_bf16 v[58:61], v[162:165], v[198:201], v[58:61]
	v_mfma_f32_16x16x32_bf16 v[46:49], v[154:157], v[206:209], v[46:49]
	v_mfma_f32_16x16x32_bf16 v[42:45], v[162:165], v[206:209], v[42:45]
	v_mfma_f32_16x16x32_bf16 v[30:33], v[154:157], v[214:217], v[30:33]
	v_mfma_f32_16x16x32_bf16 v[26:29], v[162:165], v[214:217], v[26:29]
	v_mfma_f32_16x16x32_bf16 v[14:17], v[154:157], v[222:225], v[14:17]
	v_mfma_f32_16x16x32_bf16 v[10:13], v[162:165], v[222:225], v[10:13]
	v_mfma_f32_16x16x32_bf16 v[62:65], v[158:161], v[202:205], v[62:65]
	v_mfma_f32_16x16x32_bf16 v[58:61], v[166:169], v[202:205], v[58:61]
	v_mfma_f32_16x16x32_bf16 v[46:49], v[158:161], v[210:213], v[46:49]
	v_mfma_f32_16x16x32_bf16 v[42:45], v[166:169], v[210:213], v[42:45]
	v_mfma_f32_16x16x32_bf16 v[30:33], v[158:161], v[218:221], v[30:33]
	v_mfma_f32_16x16x32_bf16 v[26:29], v[166:169], v[218:221], v[26:29]
	v_mfma_f32_16x16x32_bf16 v[14:17], v[158:161], v[226:229], v[14:17]
	v_mfma_f32_16x16x32_bf16 v[10:13], v[166:169], v[226:229], v[10:13]
	v_mfma_f32_16x16x32_bf16 v[54:57], v[182:185], v[198:201], v[54:57]
	v_mfma_f32_16x16x32_bf16 v[50:53], v[190:193], v[198:201], v[50:53]
	v_mfma_f32_16x16x32_bf16 v[38:41], v[182:185], v[206:209], v[38:41]
	v_mfma_f32_16x16x32_bf16 v[34:37], v[190:193], v[206:209], v[34:37]
	v_mfma_f32_16x16x32_bf16 v[22:25], v[182:185], v[214:217], v[22:25]
	v_mfma_f32_16x16x32_bf16 v[18:21], v[190:193], v[214:217], v[18:21]
	v_mfma_f32_16x16x32_bf16 v[6:9], v[182:185], v[222:225], v[6:9]
	v_mfma_f32_16x16x32_bf16 v[2:5], v[190:193], v[222:225], v[2:5]
	v_mfma_f32_16x16x32_bf16 v[54:57], v[186:189], v[202:205], v[54:57]
	v_mfma_f32_16x16x32_bf16 v[50:53], v[194:197], v[202:205], v[50:53]
	v_mfma_f32_16x16x32_bf16 v[38:41], v[186:189], v[210:213], v[38:41]
	v_mfma_f32_16x16x32_bf16 v[34:37], v[194:197], v[210:213], v[34:37]
	v_mfma_f32_16x16x32_bf16 v[22:25], v[186:189], v[218:221], v[22:25]
	v_mfma_f32_16x16x32_bf16 v[18:21], v[194:197], v[218:221], v[18:21]
	v_mfma_f32_16x16x32_bf16 v[6:9], v[186:189], v[226:229], v[6:9]
	v_mfma_f32_16x16x32_bf16 v[2:5], v[194:197], v[226:229], v[2:5]
	s_barrier
; #define PG8_STAGE(bufoff, gbase, voff) do { _Pragma("unroll") for (int _i = 0; _i < 2; ++_i) \
;         __builtin_amdgcn_global_load_lds((const unsigned*)((const char*)(gbase) + (voff)[_i]), (LAS unsigned*)(lds + (bufoff) + ldsw + _i * 8192), 16, 0, 0); } while (0)
; #define PG8_LDA(dst, b, h) do { _Pragma("unroll") for (int m = 0; m < 4; ++m) _Pragma("unroll") for (int k = 0; k < 2; ++k) dst[m][k] = *(const LAS bf16x8*)(lds + PG8_SA(b, h) + aoff + m * 2048 + k * 1024); } while (0)
; #define PG8_LDB(dst, b, h) do { _Pragma("unroll") for (int n = 0; n < 2; ++n) _Pragma("unroll") for (int k = 0; k < 2; ++k) dst[n][k] = *(const LAS bf16x8*)(lds + PG8_SB(b, h) + boff + n * 2048 + k * 1024); } while (0)
; #define PG8_MMA(ai, bj, At, Bt) do { __builtin_amdgcn_s_setprio(1); _Pragma("unroll") for (int m = 0; m < 4; ++m) _Pragma("unroll") for (int n = 0; n < 2; ++n) _Pragma("unroll") for (int k = 0; k < 2; ++k) \
;         acc[ai][bj][m][n] = __builtin_amdgcn_mfma_f32_16x16x32_bf16(Bt[n][k], At[m][k], acc[ai][bj][m][n], 0, 0, 0); __builtin_amdgcn_s_setprio(0); } while (0)
; #define PG8_WAIT_V(n) asm volatile("s_waitcnt vmcnt(" #n ")" ::: "memory")
; #define PG8_WAIT_L(n) asm volatile("s_waitcnt lgkmcnt(" #n ")" ::: "memory")
; #define PG8_BAR __builtin_amdgcn_s_barrier()
; #define PG8_SCHED __builtin_amdgcn_sched_barrier(0)
; template <class Epi>
; __device__ __forceinline__ void gemm_phase(LAS unsigned char* lds, const Gemm g, const StaticOrder& S, const Epi& E) {
;     ...
;             PG8_LDB(B0, 1, 0); PG8_LDB(B1, 1, 1); PG8_SCHED; PG8_LDA(At, 1, 0); PG8_STAGE(PG8_SA(0, 1), a2 + hstep, voffA);
;             PG8_WAIT_V(8); PG8_WAIT_L(0); PG8_BAR; PG8_MMA(0, 0, At, B0); PG8_MMA(0, 1, At, B1); PG8_BAR; PG8_SCHED;
;             PG8_LDA(At, 1, 1); PG8_STAGE(PG8_SB(1, 0), b3, voffB); PG8_STAGE(PG8_SB(1, 1), b3 + hstep, voffB); PG8_STAGE(PG8_SA(1, 0), a3, voffA);
;             PG8_WAIT_V(8); PG8_WAIT_L(0); PG8_BAR; PG8_MMA(1, 0, At, B0); PG8_MMA(1, 1, At, B1); PG8_BAR; PG8_SCHED;
;         }
	s_setprio 0
	s_add_i32 s76, 0, 0x18000
	v_add_u32_e32 v138, s76, v172
	s_add_i32 s77, 0, 0x1c000
	ds_read_b128 v[154:157], v138
	ds_read_b128 v[158:161], v138 offset:1024
	ds_read_b128 v[162:165], v138 offset:2048
	ds_read_b128 v[166:169], v138 offset:3072
	v_add_u32_e32 v138, s77, v172
	ds_read_b128 v[182:185], v138
	ds_read_b128 v[186:189], v138 offset:1024
	ds_read_b128 v[190:193], v138 offset:2048
	ds_read_b128 v[194:197], v138 offset:3072
	s_add_u32 s48, s48, 0x40000
	s_addc_u32 s49, s49, 0
	s_mov_b32 m0, s52
	ds_read_b128 v[198:201], v176 offset:32768
	ds_read_b128 v[202:205], v176 offset:33792
	ds_read_b128 v[206:209], v176 offset:34816
	ds_read_b128 v[210:213], v176 offset:35840
	ds_read_b128 v[214:217], v176 offset:36864
	ds_read_b128 v[218:221], v176 offset:37888
	ds_read_b128 v[222:225], v176 offset:38912
	ds_read_b128 v[226:229], v176 offset:39936
	global_load_lds_dwordx4 v130, s[48:49]
	s_mov_b32 m0, s53
	s_nop 0
	global_load_lds_dwordx4 v134, s[48:49]
	s_waitcnt vmcnt(8)
	s_waitcnt lgkmcnt(0)
	s_setprio 1
	s_barrier
	v_mfma_f32_16x16x32_bf16 v[126:129], v[154:157], v[198:201], v[126:129]
	v_mfma_f32_16x16x32_bf16 v[122:125], v[162:165], v[198:201], v[122:125]
	v_mfma_f32_16x16x32_bf16 v[110:113], v[154:157], v[206:209], v[110:113]
	v_mfma_f32_16x16x32_bf16 v[106:109], v[162:165], v[206:209], v[106:109]
	v_mfma_f32_16x16x32_bf16 v[94:97], v[154:157], v[214:217], v[94:97]
	v_mfma_f32_16x16x32_bf16 v[90:93], v[162:165], v[214:217], v[90:93]
	v_mfma_f32_16x16x32_bf16 v[78:81], v[154:157], v[222:225], v[78:81]
	v_mfma_f32_16x16x32_bf16 v[74:77], v[162:165], v[222:225], v[74:77]
	v_mfma_f32_16x16x32_bf16 v[126:129], v[158:161], v[202:205], v[126:129]
	v_mfma_f32_16x16x32_bf16 v[122:125], v[166:169], v[202:205], v[122:125]
	v_mfma_f32_16x16x32_bf16 v[110:113], v[158:161], v[210:213], v[110:113]
	v_mfma_f32_16x16x32_bf16 v[106:109], v[166:169], v[210:213], v[106:109]
	v_mfma_f32_16x16x32_bf16 v[94:97], v[158:161], v[218:221], v[94:97]
	v_mfma_f32_16x16x32_bf16 v[90:93], v[166:169], v[218:221], v[90:93]
	v_mfma_f32_16x16x32_bf16 v[78:81], v[158:161], v[226:229], v[78:81]
	v_mfma_f32_16x16x32_bf16 v[74:77], v[166:169], v[226:229], v[74:77]
	v_mfma_f32_16x16x32_bf16 v[118:121], v[182:185], v[198:201], v[118:121]
	v_mfma_f32_16x16x32_bf16 v[114:117], v[190:193], v[198:201], v[114:117]
	v_mfma_f32_16x16x32_bf16 v[102:105], v[182:185], v[206:209], v[102:105]
	v_mfma_f32_16x16x32_bf16 v[98:101], v[190:193], v[206:209], v[98:101]
	v_mfma_f32_16x16x32_bf16 v[86:89], v[182:185], v[214:217], v[86:89]
	v_mfma_f32_16x16x32_bf16 v[82:85], v[190:193], v[214:217], v[82:85]
	v_mfma_f32_16x16x32_bf16 v[70:73], v[182:185], v[222:225], v[70:73]
	v_mfma_f32_16x16x32_bf16 v[66:69], v[190:193], v[222:225], v[66:69]
	v_mfma_f32_16x16x32_bf16 v[118:121], v[186:189], v[202:205], v[118:121]
	v_mfma_f32_16x16x32_bf16 v[114:117], v[194:197], v[202:205], v[114:117]
	v_mfma_f32_16x16x32_bf16 v[102:105], v[186:189], v[210:213], v[102:105]
	v_mfma_f32_16x16x32_bf16 v[98:101], v[194:197], v[210:213], v[98:101]
	v_mfma_f32_16x16x32_bf16 v[86:89], v[186:189], v[218:221], v[86:89]
	v_mfma_f32_16x16x32_bf16 v[82:85], v[194:197], v[218:221], v[82:85]
	v_mfma_f32_16x16x32_bf16 v[70:73], v[186:189], v[226:229], v[70:73]
	v_mfma_f32_16x16x32_bf16 v[66:69], v[194:197], v[226:229], v[66:69]
	s_barrier
	s_setprio 0
	s_add_i32 s48, s76, s6
	s_mov_b32 m0, s48
	ds_read_b128 v[198:201], v176 offset:49152
	ds_read_b128 v[202:205], v176 offset:50176
	ds_read_b128 v[206:209], v176 offset:51200
	ds_read_b128 v[210:213], v176 offset:52224
	ds_read_b128 v[214:217], v176 offset:53248
	ds_read_b128 v[218:221], v176 offset:54272
	ds_read_b128 v[222:225], v176 offset:55296
	ds_read_b128 v[226:229], v176 offset:56320
	global_load_lds_dwordx4 v132, s[98:99]
	s_add_i32 m0, s48, 0x2000
	s_add_u32 s46, s46, 0x40080
	s_addc_u32 s47, s47, 0
	s_add_i32 s48, s77, s6
	global_load_lds_dwordx4 v136, s[98:99]
	s_mov_b32 m0, s48
	s_nop 0
	global_load_lds_dwordx4 v132, s[46:47]
	s_add_i32 m0, s48, 0x2000
	s_nop 0
	global_load_lds_dwordx4 v136, s[46:47]
	s_mov_b32 m0, s56
	s_nop 0
	global_load_lds_dwordx4 v130, s[100:101]
	s_mov_b32 m0, s57
	s_nop 0
	global_load_lds_dwordx4 v134, s[100:101]
	s_waitcnt vmcnt(8)
	s_waitcnt lgkmcnt(0)
	s_setprio 1
	s_barrier
	v_mfma_f32_16x16x32_bf16 v[62:65], v[154:157], v[198:201], v[62:65]
	v_mfma_f32_16x16x32_bf16 v[58:61], v[162:165], v[198:201], v[58:61]
	v_mfma_f32_16x16x32_bf16 v[46:49], v[154:157], v[206:209], v[46:49]
	v_mfma_f32_16x16x32_bf16 v[42:45], v[162:165], v[206:209], v[42:45]
	v_mfma_f32_16x16x32_bf16 v[30:33], v[154:157], v[214:217], v[30:33]
	v_mfma_f32_16x16x32_bf16 v[26:29], v[162:165], v[214:217], v[26:29]
	v_mfma_f32_16x16x32_bf16 v[14:17], v[154:157], v[222:225], v[14:17]
	v_mfma_f32_16x16x32_bf16 v[10:13], v[162:165], v[222:225], v[10:13]
	v_mfma_f32_16x16x32_bf16 v[62:65], v[158:161], v[202:205], v[62:65]
	v_mfma_f32_16x16x32_bf16 v[58:61], v[166:169], v[202:205], v[58:61]
	v_mfma_f32_16x16x32_bf16 v[46:49], v[158:161], v[210:213], v[46:49]
	v_mfma_f32_16x16x32_bf16 v[42:45], v[166:169], v[210:213], v[42:45]
	v_mfma_f32_16x16x32_bf16 v[30:33], v[158:161], v[218:221], v[30:33]
	v_mfma_f32_16x16x32_bf16 v[26:29], v[166:169], v[218:221], v[26:29]
	v_mfma_f32_16x16x32_bf16 v[14:17], v[158:161], v[226:229], v[14:17]
	v_mfma_f32_16x16x32_bf16 v[10:13], v[166:169], v[226:229], v[10:13]
	v_mfma_f32_16x16x32_bf16 v[54:57], v[182:185], v[198:201], v[54:57]
	v_mfma_f32_16x16x32_bf16 v[50:53], v[190:193], v[198:201], v[50:53]
	v_mfma_f32_16x16x32_bf16 v[38:41], v[182:185], v[206:209], v[38:41]
	v_mfma_f32_16x16x32_bf16 v[34:37], v[190:193], v[206:209], v[34:37]
	v_mfma_f32_16x16x32_bf16 v[22:25], v[182:185], v[214:217], v[22:25]
	v_mfma_f32_16x16x32_bf16 v[18:21], v[190:193], v[214:217], v[18:21]
	v_mfma_f32_16x16x32_bf16 v[6:9], v[182:185], v[222:225], v[6:9]
	v_mfma_f32_16x16x32_bf16 v[2:5], v[190:193], v[222:225], v[2:5]
	v_mfma_f32_16x16x32_bf16 v[54:57], v[186:189], v[202:205], v[54:57]
	v_mfma_f32_16x16x32_bf16 v[50:53], v[194:197], v[202:205], v[50:53]
	v_mfma_f32_16x16x32_bf16 v[38:41], v[186:189], v[210:213], v[38:41]
	v_mfma_f32_16x16x32_bf16 v[34:37], v[194:197], v[210:213], v[34:37]
	v_mfma_f32_16x16x32_bf16 v[22:25], v[186:189], v[218:221], v[22:25]
	v_mfma_f32_16x16x32_bf16 v[18:21], v[194:197], v[218:221], v[18:21]
	v_mfma_f32_16x16x32_bf16 v[6:9], v[186:189], v[226:229], v[6:9]
	v_mfma_f32_16x16x32_bf16 v[2:5], v[194:197], v[226:229], v[2:5]
	s_barrier
	s_setprio 0
	s_add_i32 s69, s69, 2
	s_add_u32 s44, s44, 0x100
	s_addc_u32 s45, s45, 0
	s_add_u32 s67, s67, 0x100
	s_addc_u32 s68, s68, 0
	s_cmp_gt_u32 s69, 13
	s_cbranch_scc0 .LBB0_619
	s_and_b64 vcc, exec, s[18:19]
	s_cbranch_vccz .LBB0_622
	s_barrier

; #define PG8_STAGE(bufoff, gbase, voff) do { _Pragma("unroll") for (int _i = 0; _i < 2; ++_i) \
;         __builtin_amdgcn_global_load_lds((const unsigned*)((const char*)(gbase) + (voff)[_i]), (LAS unsigned*)(lds + (bufoff) + ldsw + _i * 8192), 16, 0, 0); } while (0)
; #define PG8_LDA(dst, b, h) do { _Pragma("unroll") for (int m = 0; m < 4; ++m) _Pragma("unroll") for (int k = 0; k < 2; ++k) dst[m][k] = *(const LAS bf16x8*)(lds + PG8_SA(b, h) + aoff + m * 2048 + k * 1024); } while (0)
; #define PG8_LDB(dst, b, h) do { _Pragma("unroll") for (int n = 0; n < 2; ++n) _Pragma("unroll") for (int k = 0; k < 2; ++k) dst[n][k] = *(const LAS bf16x8*)(lds + PG8_SB(b, h) + boff + n * 2048 + k * 1024); } while (0)
; #define PG8_MMA(ai, bj, At, Bt) do { __builtin_amdgcn_s_setprio(1); _Pragma("unroll") for (int m = 0; m < 4; ++m) _Pragma("unroll") for (int n = 0; n < 2; ++n) _Pragma("unroll") for (int k = 0; k < 2; ++k) \
;         acc[ai][bj][m][n] = __builtin_amdgcn_mfma_f32_16x16x32_bf16(Bt[n][k], At[m][k], acc[ai][bj][m][n], 0, 0, 0); __builtin_amdgcn_s_setprio(0); } while (0)
; #define PG8_WAIT_V(n) asm volatile("s_waitcnt vmcnt(" #n ")" ::: "memory")
; #define PG8_WAIT_L(n) asm volatile("s_waitcnt lgkmcnt(" #n ")" ::: "memory")
; #define PG8_BAR __builtin_amdgcn_s_barrier()
; template <class Epi>
; __device__ __forceinline__ void gemm_phase(LAS unsigned char* lds, const Gemm g, const StaticOrder& S, const Epi& E) {
;     ...
;             const bool last = (t == nt - 2);
;             const char* a1 = cA + (size_t)(t + 1) * kstep;
;             const char* a2 = last ? nA : cA + (size_t)(t + 2) * kstep; const char* b2 = last ? nB : cB + (size_t)(t + 2) * kstep;
;             const char* a3 = a2 + kstep; const char* b3 = b2 + kstep;
;             if constexpr (Epi::MIDK > 0) { if (t == Epi::MIDK) E.mid(acc, cur, wr, wc, fr, fq); }
;             PG8_LDB(B0, 0, 0); PG8_LDB(B1, 0, 1); PG8_SCHED; PG8_LDA(At, 0, 0); PG8_STAGE(PG8_SA(1, 1), a1 + hstep, voffA);
;             PG8_WAIT_V(8); PG8_WAIT_L(0); PG8_BAR; PG8_MMA(0, 0, At, B0); PG8_MMA(0, 1, At, B1); PG8_BAR; PG8_SCHED;
;             PG8_LDA(At, 0, 1); PG8_STAGE(PG8_SB(0, 0), b2, voffB); PG8_STAGE(PG8_SB(0, 1), b2 + hstep, voffB); PG8_STAGE(PG8_SA(0, 0), a2, voffA);
;             PG8_WAIT_V(8); PG8_WAIT_L(0); PG8_BAR; PG8_MMA(1, 0, At, B0); PG8_MMA(1, 1, At, B1); PG8_BAR; PG8_SCHED;
.LBB0_884:
	ds_read_b128 v[158:161], v150
	ds_read_b128 v[162:165], v150 offset:1024
	ds_read_b128 v[166:169], v150 offset:2048
	ds_read_b128 v[174:177], v150 offset:3072
	ds_read_b128 v[178:181], v151
	ds_read_b128 v[182:185], v151 offset:1024
	ds_read_b128 v[186:189], v151 offset:2048
	ds_read_b128 v[190:193], v151 offset:3072
	s_add_u32 s46, s44, 0xfffc0080
	s_addc_u32 s47, s45, -1
	s_cmp_eq_u32 s67, 12
	s_cselect_b32 s49, s62, s47
	s_cselect_b32 s48, s63, s46
	s_cselect_b32 s47, s23, s66
	s_cselect_b32 s46, s64, s65
	s_add_i32 m0, s41, 0xc000
	ds_read_b128 v[194:197], v152
	ds_read_b128 v[198:201], v152 offset:1024
	ds_read_b128 v[202:205], v152 offset:2048
	ds_read_b128 v[206:209], v152 offset:3072
	ds_read_b128 v[210:213], v152 offset:4096
	ds_read_b128 v[214:217], v152 offset:5120
	ds_read_b128 v[218:221], v152 offset:6144
	ds_read_b128 v[222:225], v152 offset:7168
	global_load_lds_dwordx4 v140, s[44:45]
	s_add_i32 m0, s41, 0xe000
	s_nop 0
	global_load_lds_dwordx4 v142, s[44:45]
	s_waitcnt vmcnt(8)
	s_waitcnt lgkmcnt(0)
	s_setprio 1
	s_barrier
	v_mfma_f32_16x16x32_bf16 v[126:129], v[158:161], v[194:197], v[126:129]
	v_mfma_f32_16x16x32_bf16 v[118:121], v[166:169], v[194:197], v[118:121]
	v_mfma_f32_16x16x32_bf16 v[110:113], v[158:161], v[202:205], v[110:113]
	v_mfma_f32_16x16x32_bf16 v[102:105], v[166:169], v[202:205], v[102:105]
	v_mfma_f32_16x16x32_bf16 v[94:97], v[158:161], v[210:213], v[94:97]
	v_mfma_f32_16x16x32_bf16 v[86:89], v[166:169], v[210:213], v[86:89]
	v_mfma_f32_16x16x32_bf16 v[78:81], v[158:161], v[218:221], v[78:81]
	v_mfma_f32_16x16x32_bf16 v[70:73], v[166:169], v[218:221], v[70:73]
	v_mfma_f32_16x16x32_bf16 v[126:129], v[162:165], v[198:201], v[126:129]
	v_mfma_f32_16x16x32_bf16 v[118:121], v[174:177], v[198:201], v[118:121]
	v_mfma_f32_16x16x32_bf16 v[110:113], v[162:165], v[206:209], v[110:113]
	v_mfma_f32_16x16x32_bf16 v[102:105], v[174:177], v[206:209], v[102:105]
	v_mfma_f32_16x16x32_bf16 v[94:97], v[162:165], v[214:217], v[94:97]
	v_mfma_f32_16x16x32_bf16 v[86:89], v[174:177], v[214:217], v[86:89]
	v_mfma_f32_16x16x32_bf16 v[78:81], v[162:165], v[222:225], v[78:81]
	v_mfma_f32_16x16x32_bf16 v[70:73], v[174:177], v[222:225], v[70:73]
	v_mfma_f32_16x16x32_bf16 v[122:125], v[178:181], v[194:197], v[122:125]
	v_mfma_f32_16x16x32_bf16 v[114:117], v[186:189], v[194:197], v[114:117]
	v_mfma_f32_16x16x32_bf16 v[106:109], v[178:181], v[202:205], v[106:109]
	v_mfma_f32_16x16x32_bf16 v[98:101], v[186:189], v[202:205], v[98:101]
	v_mfma_f32_16x16x32_bf16 v[90:93], v[178:181], v[210:213], v[90:93]
	v_mfma_f32_16x16x32_bf16 v[82:85], v[186:189], v[210:213], v[82:85]
	v_mfma_f32_16x16x32_bf16 v[74:77], v[178:181], v[218:221], v[74:77]
	v_mfma_f32_16x16x32_bf16 v[66:69], v[186:189], v[218:221], v[66:69]
	v_mfma_f32_16x16x32_bf16 v[122:125], v[182:185], v[198:201], v[122:125]
	v_mfma_f32_16x16x32_bf16 v[114:117], v[190:193], v[198:201], v[114:117]
	v_mfma_f32_16x16x32_bf16 v[106:109], v[182:185], v[206:209], v[106:109]
	v_mfma_f32_16x16x32_bf16 v[98:101], v[190:193], v[206:209], v[98:101]
	v_mfma_f32_16x16x32_bf16 v[90:93], v[182:185], v[214:217], v[90:93]
	v_mfma_f32_16x16x32_bf16 v[82:85], v[190:193], v[214:217], v[82:85]
	v_mfma_f32_16x16x32_bf16 v[74:77], v[182:185], v[222:225], v[74:77]
	v_mfma_f32_16x16x32_bf16 v[66:69], v[190:193], v[222:225], v[66:69]
	s_barrier
	s_setprio 0
	s_add_u32 s98, s46, s8
	s_addc_u32 s99, s47, s9
	s_add_u32 s100, s48, s8
	s_addc_u32 s101, s49, s9
	s_add_i32 s68, s58, s6
	s_mov_b32 m0, s68
	ds_read_b128 v[194:197], v152 offset:16384
	ds_read_b128 v[198:201], v152 offset:17408
	ds_read_b128 v[202:205], v152 offset:18432
	ds_read_b128 v[206:209], v152 offset:19456
	ds_read_b128 v[210:213], v152 offset:20480
	ds_read_b128 v[214:217], v152 offset:21504
	ds_read_b128 v[218:221], v152 offset:22528
	ds_read_b128 v[222:225], v152 offset:23552
	global_load_lds_dwordx4 v132, s[46:47]
	s_add_i32 m0, s68, 0x2000
	s_add_u32 s68, s46, 0x40000
	s_addc_u32 s69, s47, 0
	s_add_i32 s76, s59, s6
	global_load_lds_dwordx4 v136, s[46:47]
	s_mov_b32 m0, s76
	s_nop 0
	global_load_lds_dwordx4 v132, s[68:69]
	s_add_i32 m0, s76, 0x2000
	s_nop 0
	global_load_lds_dwordx4 v136, s[68:69]
	s_mov_b32 m0, s41
	s_nop 0
	global_load_lds_dwordx4 v130, s[48:49]
	s_mov_b32 m0, s43
	s_nop 0
	global_load_lds_dwordx4 v134, s[48:49]
	s_waitcnt vmcnt(8)
	s_waitcnt lgkmcnt(0)
	s_setprio 1
	s_barrier
	v_mfma_f32_16x16x32_bf16 v[62:65], v[158:161], v[194:197], v[62:65]
	v_mfma_f32_16x16x32_bf16 v[54:57], v[166:169], v[194:197], v[54:57]
	v_mfma_f32_16x16x32_bf16 v[46:49], v[158:161], v[202:205], v[46:49]
	v_mfma_f32_16x16x32_bf16 v[38:41], v[166:169], v[202:205], v[38:41]
	v_mfma_f32_16x16x32_bf16 v[30:33], v[158:161], v[210:213], v[30:33]
	v_mfma_f32_16x16x32_bf16 v[22:25], v[166:169], v[210:213], v[22:25]
	v_mfma_f32_16x16x32_bf16 v[14:17], v[158:161], v[218:221], v[14:17]
	v_mfma_f32_16x16x32_bf16 v[6:9], v[166:169], v[218:221], v[6:9]
	v_mfma_f32_16x16x32_bf16 v[62:65], v[162:165], v[198:201], v[62:65]
	v_mfma_f32_16x16x32_bf16 v[54:57], v[174:177], v[198:201], v[54:57]
	v_mfma_f32_16x16x32_bf16 v[46:49], v[162:165], v[206:209], v[46:49]
	v_mfma_f32_16x16x32_bf16 v[38:41], v[174:177], v[206:209], v[38:41]
	v_mfma_f32_16x16x32_bf16 v[30:33], v[162:165], v[214:217], v[30:33]
	v_mfma_f32_16x16x32_bf16 v[22:25], v[174:177], v[214:217], v[22:25]
	v_mfma_f32_16x16x32_bf16 v[14:17], v[162:165], v[222:225], v[14:17]
	v_mfma_f32_16x16x32_bf16 v[6:9], v[174:177], v[222:225], v[6:9]
	v_mfma_f32_16x16x32_bf16 v[58:61], v[178:181], v[194:197], v[58:61]
	v_mfma_f32_16x16x32_bf16 v[50:53], v[186:189], v[194:197], v[50:53]
	v_mfma_f32_16x16x32_bf16 v[42:45], v[178:181], v[202:205], v[42:45]
	v_mfma_f32_16x16x32_bf16 v[34:37], v[186:189], v[202:205], v[34:37]
	v_mfma_f32_16x16x32_bf16 v[26:29], v[178:181], v[210:213], v[26:29]
	v_mfma_f32_16x16x32_bf16 v[18:21], v[186:189], v[210:213], v[18:21]
	v_mfma_f32_16x16x32_bf16 v[10:13], v[178:181], v[218:221], v[10:13]
	v_mfma_f32_16x16x32_bf16 v[2:5], v[186:189], v[218:221], v[2:5]
	v_mfma_f32_16x16x32_bf16 v[58:61], v[182:185], v[198:201], v[58:61]
	v_mfma_f32_16x16x32_bf16 v[50:53], v[190:193], v[198:201], v[50:53]
	v_mfma_f32_16x16x32_bf16 v[42:45], v[182:185], v[206:209], v[42:45]
	v_mfma_f32_16x16x32_bf16 v[34:37], v[190:193], v[206:209], v[34:37]
	v_mfma_f32_16x16x32_bf16 v[26:29], v[182:185], v[214:217], v[26:29]
	v_mfma_f32_16x16x32_bf16 v[18:21], v[190:193], v[214:217], v[18:21]
	v_mfma_f32_16x16x32_bf16 v[10:13], v[182:185], v[222:225], v[10:13]
	v_mfma_f32_16x16x32_bf16 v[2:5], v[190:193], v[222:225], v[2:5]
	s_barrier
; #define PG8_STAGE(bufoff, gbase, voff) do { _Pragma("unroll") for (int _i = 0; _i < 2; ++_i) \
;         __builtin_amdgcn_global_load_lds((const unsigned*)((const char*)(gbase) + (voff)[_i]), (LAS unsigned*)(lds + (bufoff) + ldsw + _i * 8192), 16, 0, 0); } while (0)
; #define PG8_LDA(dst, b, h) do { _Pragma("unroll") for (int m = 0; m < 4; ++m) _Pragma("unroll") for (int k = 0; k < 2; ++k) dst[m][k] = *(const LAS bf16x8*)(lds + PG8_SA(b, h) + aoff + m * 2048 + k * 1024); } while (0)
; #define PG8_LDB(dst, b, h) do { _Pragma("unroll") for (int n = 0; n < 2; ++n) _Pragma("unroll") for (int k = 0; k < 2; ++k) dst[n][k] = *(const LAS bf16x8*)(lds + PG8_SB(b, h) + boff + n * 2048 + k * 1024); } while (0)
; #define PG8_MMA(ai, bj, At, Bt) do { __builtin_amdgcn_s_setprio(1); _Pragma("unroll") for (int m = 0; m < 4; ++m) _Pragma("unroll") for (int n = 0; n < 2; ++n) _Pragma("unroll") for (int k = 0; k < 2; ++k) \
;         acc[ai][bj][m][n] = __builtin_amdgcn_mfma_f32_16x16x32_bf16(Bt[n][k], At[m][k], acc[ai][bj][m][n], 0, 0, 0); __builtin_amdgcn_s_setprio(0); } while (0)
; #define PG8_WAIT_V(n) asm volatile("s_waitcnt vmcnt(" #n ")" ::: "memory")
; #define PG8_WAIT_L(n) asm volatile("s_waitcnt lgkmcnt(" #n ")" ::: "memory")
; #define PG8_BAR __builtin_amdgcn_s_barrier()
; #define PG8_SCHED __builtin_amdgcn_sched_barrier(0)
; template <class Epi>
; __device__ __forceinline__ void gemm_phase(LAS unsigned char* lds, const Gemm g, const StaticOrder& S, const Epi& E) {
;     ...
;             PG8_LDB(B0, 1, 0); PG8_LDB(B1, 1, 1); PG8_SCHED; PG8_LDA(At, 1, 0); PG8_STAGE(PG8_SA(0, 1), a2 + hstep, voffA);
;             PG8_WAIT_V(8); PG8_WAIT_L(0); PG8_BAR; PG8_MMA(0, 0, At, B0); PG8_MMA(0, 1, At, B1); PG8_BAR; PG8_SCHED;
;             PG8_LDA(At, 1, 1); PG8_STAGE(PG8_SB(1, 0), b3, voffB); PG8_STAGE(PG8_SB(1, 1), b3 + hstep, voffB); PG8_STAGE(PG8_SA(1, 0), a3, voffA);
;             PG8_WAIT_V(8); PG8_WAIT_L(0); PG8_BAR; PG8_MMA(1, 0, At, B0); PG8_MMA(1, 1, At, B1); PG8_BAR; PG8_SCHED;
;         }
	s_setprio 0
	s_add_i32 s68, 0, 0x18000
	s_add_i32 s69, 0, 0x1c000
	v_add_u32_e32 v174, s68, v148
	v_add_u32_e32 v190, s69, v148
	ds_read_b128 v[158:161], v174
	ds_read_b128 v[162:165], v174 offset:1024
	ds_read_b128 v[166:169], v174 offset:2048
	ds_read_b128 v[174:177], v174 offset:3072
	ds_read_b128 v[178:181], v190
	ds_read_b128 v[182:185], v190 offset:1024
	ds_read_b128 v[186:189], v190 offset:2048
	ds_read_b128 v[190:193], v190 offset:3072
	s_add_u32 s48, s48, 0x40000
	s_addc_u32 s49, s49, 0
	s_mov_b32 m0, s51
	ds_read_b128 v[194:197], v152 offset:32768
	ds_read_b128 v[198:201], v152 offset:33792
	ds_read_b128 v[202:205], v152 offset:34816
	ds_read_b128 v[206:209], v152 offset:35840
	ds_read_b128 v[210:213], v152 offset:36864
	ds_read_b128 v[214:217], v152 offset:37888
	ds_read_b128 v[218:221], v152 offset:38912
	ds_read_b128 v[222:225], v152 offset:39936
	global_load_lds_dwordx4 v130, s[48:49]
	s_mov_b32 m0, s52
	s_nop 0
	global_load_lds_dwordx4 v134, s[48:49]
	s_waitcnt vmcnt(8)
	s_waitcnt lgkmcnt(0)
	s_setprio 1
	s_barrier
	v_mfma_f32_16x16x32_bf16 v[126:129], v[158:161], v[194:197], v[126:129]
	v_mfma_f32_16x16x32_bf16 v[118:121], v[166:169], v[194:197], v[118:121]
	v_mfma_f32_16x16x32_bf16 v[110:113], v[158:161], v[202:205], v[110:113]
	v_mfma_f32_16x16x32_bf16 v[102:105], v[166:169], v[202:205], v[102:105]
	v_mfma_f32_16x16x32_bf16 v[94:97], v[158:161], v[210:213], v[94:97]
	v_mfma_f32_16x16x32_bf16 v[86:89], v[166:169], v[210:213], v[86:89]
	v_mfma_f32_16x16x32_bf16 v[78:81], v[158:161], v[218:221], v[78:81]
	v_mfma_f32_16x16x32_bf16 v[70:73], v[166:169], v[218:221], v[70:73]
	v_mfma_f32_16x16x32_bf16 v[126:129], v[162:165], v[198:201], v[126:129]
	v_mfma_f32_16x16x32_bf16 v[118:121], v[174:177], v[198:201], v[118:121]
	v_mfma_f32_16x16x32_bf16 v[110:113], v[162:165], v[206:209], v[110:113]
	v_mfma_f32_16x16x32_bf16 v[102:105], v[174:177], v[206:209], v[102:105]
	v_mfma_f32_16x16x32_bf16 v[94:97], v[162:165], v[214:217], v[94:97]
	v_mfma_f32_16x16x32_bf16 v[86:89], v[174:177], v[214:217], v[86:89]
	v_mfma_f32_16x16x32_bf16 v[78:81], v[162:165], v[222:225], v[78:81]
	v_mfma_f32_16x16x32_bf16 v[70:73], v[174:177], v[222:225], v[70:73]
	v_mfma_f32_16x16x32_bf16 v[122:125], v[178:181], v[194:197], v[122:125]
	v_mfma_f32_16x16x32_bf16 v[114:117], v[186:189], v[194:197], v[114:117]
	v_mfma_f32_16x16x32_bf16 v[106:109], v[178:181], v[202:205], v[106:109]
	v_mfma_f32_16x16x32_bf16 v[98:101], v[186:189], v[202:205], v[98:101]
	v_mfma_f32_16x16x32_bf16 v[90:93], v[178:181], v[210:213], v[90:93]
	v_mfma_f32_16x16x32_bf16 v[82:85], v[186:189], v[210:213], v[82:85]
	v_mfma_f32_16x16x32_bf16 v[74:77], v[178:181], v[218:221], v[74:77]
	v_mfma_f32_16x16x32_bf16 v[66:69], v[186:189], v[218:221], v[66:69]
	v_mfma_f32_16x16x32_bf16 v[122:125], v[182:185], v[198:201], v[122:125]
	v_mfma_f32_16x16x32_bf16 v[114:117], v[190:193], v[198:201], v[114:117]
	v_mfma_f32_16x16x32_bf16 v[106:109], v[182:185], v[206:209], v[106:109]
	v_mfma_f32_16x16x32_bf16 v[98:101], v[190:193], v[206:209], v[98:101]
	v_mfma_f32_16x16x32_bf16 v[90:93], v[182:185], v[214:217], v[90:93]
	v_mfma_f32_16x16x32_bf16 v[82:85], v[190:193], v[214:217], v[82:85]
	v_mfma_f32_16x16x32_bf16 v[74:77], v[182:185], v[222:225], v[74:77]
	v_mfma_f32_16x16x32_bf16 v[66:69], v[190:193], v[222:225], v[66:69]
	s_barrier
	s_setprio 0
	s_add_i32 s48, s68, s6
	s_mov_b32 m0, s48
	ds_read_b128 v[194:197], v152 offset:49152
	ds_read_b128 v[198:201], v152 offset:50176
	ds_read_b128 v[202:205], v152 offset:51200
	ds_read_b128 v[206:209], v152 offset:52224
	ds_read_b128 v[210:213], v152 offset:53248
	ds_read_b128 v[214:217], v152 offset:54272
	ds_read_b128 v[218:221], v152 offset:55296
	ds_read_b128 v[222:225], v152 offset:56320
	global_load_lds_dwordx4 v132, s[98:99]
	s_add_i32 m0, s48, 0x2000
	s_add_u32 s46, s46, 0x40080
	s_addc_u32 s47, s47, 0
	s_add_i32 s48, s69, s6
	global_load_lds_dwordx4 v136, s[98:99]
	s_mov_b32 m0, s48
	s_nop 0
	global_load_lds_dwordx4 v132, s[46:47]
	s_add_i32 m0, s48, 0x2000
	s_nop 0
	global_load_lds_dwordx4 v136, s[46:47]
	s_mov_b32 m0, s53
	s_nop 0
	global_load_lds_dwordx4 v130, s[100:101]
	s_mov_b32 m0, s54
	s_nop 0
	global_load_lds_dwordx4 v134, s[100:101]
	s_waitcnt vmcnt(8)
	s_waitcnt lgkmcnt(0)
	s_setprio 1
	s_barrier
	v_mfma_f32_16x16x32_bf16 v[62:65], v[158:161], v[194:197], v[62:65]
	v_mfma_f32_16x16x32_bf16 v[54:57], v[166:169], v[194:197], v[54:57]
	v_mfma_f32_16x16x32_bf16 v[46:49], v[158:161], v[202:205], v[46:49]
	v_mfma_f32_16x16x32_bf16 v[38:41], v[166:169], v[202:205], v[38:41]
	v_mfma_f32_16x16x32_bf16 v[30:33], v[158:161], v[210:213], v[30:33]
	v_mfma_f32_16x16x32_bf16 v[22:25], v[166:169], v[210:213], v[22:25]
	v_mfma_f32_16x16x32_bf16 v[14:17], v[158:161], v[218:221], v[14:17]
	v_mfma_f32_16x16x32_bf16 v[6:9], v[166:169], v[218:221], v[6:9]
	v_mfma_f32_16x16x32_bf16 v[62:65], v[162:165], v[198:201], v[62:65]
	v_mfma_f32_16x16x32_bf16 v[54:57], v[174:177], v[198:201], v[54:57]
	v_mfma_f32_16x16x32_bf16 v[46:49], v[162:165], v[206:209], v[46:49]
	v_mfma_f32_16x16x32_bf16 v[38:41], v[174:177], v[206:209], v[38:41]
	v_mfma_f32_16x16x32_bf16 v[30:33], v[162:165], v[214:217], v[30:33]
	v_mfma_f32_16x16x32_bf16 v[22:25], v[174:177], v[214:217], v[22:25]
	v_mfma_f32_16x16x32_bf16 v[14:17], v[162:165], v[222:225], v[14:17]
	v_mfma_f32_16x16x32_bf16 v[6:9], v[174:177], v[222:225], v[6:9]
	v_mfma_f32_16x16x32_bf16 v[58:61], v[178:181], v[194:197], v[58:61]
	v_mfma_f32_16x16x32_bf16 v[50:53], v[186:189], v[194:197], v[50:53]
	v_mfma_f32_16x16x32_bf16 v[42:45], v[178:181], v[202:205], v[42:45]
	v_mfma_f32_16x16x32_bf16 v[34:37], v[186:189], v[202:205], v[34:37]
	v_mfma_f32_16x16x32_bf16 v[26:29], v[178:181], v[210:213], v[26:29]
	v_mfma_f32_16x16x32_bf16 v[18:21], v[186:189], v[210:213], v[18:21]
	v_mfma_f32_16x16x32_bf16 v[10:13], v[178:181], v[218:221], v[10:13]
	v_mfma_f32_16x16x32_bf16 v[2:5], v[186:189], v[218:221], v[2:5]
	v_mfma_f32_16x16x32_bf16 v[58:61], v[182:185], v[198:201], v[58:61]
	v_mfma_f32_16x16x32_bf16 v[50:53], v[190:193], v[198:201], v[50:53]
	v_mfma_f32_16x16x32_bf16 v[42:45], v[182:185], v[206:209], v[42:45]
	v_mfma_f32_16x16x32_bf16 v[34:37], v[190:193], v[206:209], v[34:37]
	v_mfma_f32_16x16x32_bf16 v[26:29], v[182:185], v[214:217], v[26:29]
	v_mfma_f32_16x16x32_bf16 v[18:21], v[190:193], v[214:217], v[18:21]
	v_mfma_f32_16x16x32_bf16 v[10:13], v[182:185], v[222:225], v[10:13]
	v_mfma_f32_16x16x32_bf16 v[2:5], v[190:193], v[222:225], v[2:5]
	s_barrier
	s_setprio 0
	s_add_i32 s67, s67, 2
	s_add_u32 s44, s44, 0x100
	s_addc_u32 s45, s45, 0
	s_add_u32 s65, s65, 0x100
	s_addc_u32 s66, s66, 0
	s_cmp_gt_u32 s67, 13
	s_cbranch_scc0 .LBB0_884
	s_and_b64 vcc, exec, s[14:15]
	s_cbranch_vccz .LBB0_887
	s_barrier

; #define PG8_STAGE(bufoff, gbase, voff) do { _Pragma("unroll") for (int _i = 0; _i < 2; ++_i) \
;         __builtin_amdgcn_global_load_lds((const unsigned*)((const char*)(gbase) + (voff)[_i]), (LAS unsigned*)(lds + (bufoff) + ldsw + _i * 8192), 16, 0, 0); } while (0)
; #define PG8_LDA(dst, b, h) do { _Pragma("unroll") for (int m = 0; m < 4; ++m) _Pragma("unroll") for (int k = 0; k < 2; ++k) dst[m][k] = *(const LAS bf16x8*)(lds + PG8_SA(b, h) + aoff + m * 2048 + k * 1024); } while (0)
; #define PG8_LDB(dst, b, h) do { _Pragma("unroll") for (int n = 0; n < 2; ++n) _Pragma("unroll") for (int k = 0; k < 2; ++k) dst[n][k] = *(const LAS bf16x8*)(lds + PG8_SB(b, h) + boff + n * 2048 + k * 1024); } while (0)
; #define PG8_MMA(ai, bj, At, Bt) do { __builtin_amdgcn_s_setprio(1); _Pragma("unroll") for (int m = 0; m < 4; ++m) _Pragma("unroll") for (int n = 0; n < 2; ++n) _Pragma("unroll") for (int k = 0; k < 2; ++k) \
;         acc[ai][bj][m][n] = __builtin_amdgcn_mfma_f32_16x16x32_bf16(Bt[n][k], At[m][k], acc[ai][bj][m][n], 0, 0, 0); __builtin_amdgcn_s_setprio(0); } while (0)
; #define PG8_WAIT_V(n) asm volatile("s_waitcnt vmcnt(" #n ")" ::: "memory")
; #define PG8_WAIT_L(n) asm volatile("s_waitcnt lgkmcnt(" #n ")" ::: "memory")
; #define PG8_BAR __builtin_amdgcn_s_barrier()
; template <class Epi>
; __device__ __forceinline__ void gemm_phase(LAS unsigned char* lds, const Gemm g, const StaticOrder& S, const Epi& E) {
;     ...
;             const bool last = (t == nt - 2);
;             const char* a1 = cA + (size_t)(t + 1) * kstep;
;             const char* a2 = last ? nA : cA + (size_t)(t + 2) * kstep; const char* b2 = last ? nB : cB + (size_t)(t + 2) * kstep;
;             const char* a3 = a2 + kstep; const char* b3 = b2 + kstep;
;             if constexpr (Epi::MIDK > 0) { if (t == Epi::MIDK) E.mid(acc, cur, wr, wc, fr, fq); }
;             PG8_LDB(B0, 0, 0); PG8_LDB(B1, 0, 1); PG8_SCHED; PG8_LDA(At, 0, 0); PG8_STAGE(PG8_SA(1, 1), a1 + hstep, voffA);
;             PG8_WAIT_V(8); PG8_WAIT_L(0); PG8_BAR; PG8_MMA(0, 0, At, B0); PG8_MMA(0, 1, At, B1); PG8_BAR; PG8_SCHED;
;             PG8_LDA(At, 0, 1); PG8_STAGE(PG8_SB(0, 0), b2, voffB); PG8_STAGE(PG8_SB(0, 1), b2 + hstep, voffB); PG8_STAGE(PG8_SA(0, 0), a2, voffA);
;             PG8_WAIT_V(8); PG8_WAIT_L(0); PG8_BAR; PG8_MMA(1, 0, At, B0); PG8_MMA(1, 1, At, B1); PG8_BAR; PG8_SCHED;
.LBB0_971:
	ds_read_b128 v[130:133], v162
	ds_read_b128 v[134:137], v162 offset:1024
	ds_read_b128 v[154:157], v162 offset:2048
	ds_read_b128 v[166:169], v162 offset:3072
	ds_read_b128 v[174:177], v163
	ds_read_b128 v[178:181], v163 offset:1024
	ds_read_b128 v[182:185], v163 offset:2048
	ds_read_b128 v[186:189], v163 offset:3072
	s_add_u32 s24, s22, 0xfff50080
	s_addc_u32 s25, s23, -1
	s_cmp_eq_u32 s59, 40
	s_cselect_b32 s27, s5, s25
	s_cselect_b32 s26, s4, s24
	s_cselect_b32 s25, s21, s58
	s_cselect_b32 s24, s20, s57
	s_add_i32 m0, s39, 0xc000
	ds_read_b128 v[190:193], v164
	ds_read_b128 v[194:197], v164 offset:1024
	ds_read_b128 v[198:201], v164 offset:2048
	ds_read_b128 v[202:205], v164 offset:3072
	ds_read_b128 v[206:209], v164 offset:4096
	ds_read_b128 v[210:213], v164 offset:5120
	ds_read_b128 v[214:217], v164 offset:6144
	ds_read_b128 v[218:221], v164 offset:7168
	global_load_lds_dwordx4 v146, s[22:23]
	s_add_i32 m0, s39, 0xe000
	s_nop 0
	global_load_lds_dwordx4 v148, s[22:23]
	s_waitcnt vmcnt(8)
	s_waitcnt lgkmcnt(0)
	s_setprio 1
	s_barrier
	v_mfma_f32_16x16x32_bf16 v[126:129], v[130:133], v[190:193], v[126:129]
	v_mfma_f32_16x16x32_bf16 v[122:125], v[154:157], v[190:193], v[122:125]
	v_mfma_f32_16x16x32_bf16 v[110:113], v[130:133], v[198:201], v[110:113]
	v_mfma_f32_16x16x32_bf16 v[106:109], v[154:157], v[198:201], v[106:109]
	v_mfma_f32_16x16x32_bf16 v[94:97], v[130:133], v[206:209], v[94:97]
	v_mfma_f32_16x16x32_bf16 v[90:93], v[154:157], v[206:209], v[90:93]
	v_mfma_f32_16x16x32_bf16 v[78:81], v[130:133], v[214:217], v[78:81]
	v_mfma_f32_16x16x32_bf16 v[74:77], v[154:157], v[214:217], v[74:77]
	v_mfma_f32_16x16x32_bf16 v[126:129], v[134:137], v[194:197], v[126:129]
	v_mfma_f32_16x16x32_bf16 v[122:125], v[166:169], v[194:197], v[122:125]
	v_mfma_f32_16x16x32_bf16 v[110:113], v[134:137], v[202:205], v[110:113]
	v_mfma_f32_16x16x32_bf16 v[106:109], v[166:169], v[202:205], v[106:109]
	v_mfma_f32_16x16x32_bf16 v[94:97], v[134:137], v[210:213], v[94:97]
	v_mfma_f32_16x16x32_bf16 v[90:93], v[166:169], v[210:213], v[90:93]
	v_mfma_f32_16x16x32_bf16 v[78:81], v[134:137], v[218:221], v[78:81]
	v_mfma_f32_16x16x32_bf16 v[74:77], v[166:169], v[218:221], v[74:77]
	v_mfma_f32_16x16x32_bf16 v[118:121], v[174:177], v[190:193], v[118:121]
	v_mfma_f32_16x16x32_bf16 v[114:117], v[182:185], v[190:193], v[114:117]
	v_mfma_f32_16x16x32_bf16 v[102:105], v[174:177], v[198:201], v[102:105]
	v_mfma_f32_16x16x32_bf16 v[98:101], v[182:185], v[198:201], v[98:101]
	v_mfma_f32_16x16x32_bf16 v[86:89], v[174:177], v[206:209], v[86:89]
	v_mfma_f32_16x16x32_bf16 v[82:85], v[182:185], v[206:209], v[82:85]
	v_mfma_f32_16x16x32_bf16 v[70:73], v[174:177], v[214:217], v[70:73]
	v_mfma_f32_16x16x32_bf16 v[66:69], v[182:185], v[214:217], v[66:69]
	v_mfma_f32_16x16x32_bf16 v[118:121], v[178:181], v[194:197], v[118:121]
	v_mfma_f32_16x16x32_bf16 v[114:117], v[186:189], v[194:197], v[114:117]
	v_mfma_f32_16x16x32_bf16 v[102:105], v[178:181], v[202:205], v[102:105]
	v_mfma_f32_16x16x32_bf16 v[98:101], v[186:189], v[202:205], v[98:101]
	v_mfma_f32_16x16x32_bf16 v[86:89], v[178:181], v[210:213], v[86:89]
	v_mfma_f32_16x16x32_bf16 v[82:85], v[186:189], v[210:213], v[82:85]
	v_mfma_f32_16x16x32_bf16 v[70:73], v[178:181], v[218:221], v[70:73]
	v_mfma_f32_16x16x32_bf16 v[66:69], v[186:189], v[218:221], v[66:69]
	s_barrier
	s_setprio 0
	s_add_u32 s98, s24, s14
	s_addc_u32 s99, s25, s15
	s_add_u32 s100, s26, s14
	s_addc_u32 s101, s27, s15
	s_add_i32 s60, s51, s38
	s_mov_b32 m0, s60
	ds_read_b128 v[190:193], v164 offset:16384
	ds_read_b128 v[194:197], v164 offset:17408
	ds_read_b128 v[198:201], v164 offset:18432
	ds_read_b128 v[202:205], v164 offset:19456
	ds_read_b128 v[206:209], v164 offset:20480
	ds_read_b128 v[210:213], v164 offset:21504
	ds_read_b128 v[214:217], v164 offset:22528
	ds_read_b128 v[218:221], v164 offset:23552
	global_load_lds_dwordx4 v140, s[24:25]
	s_add_i32 m0, s60, 0x2000
	s_add_u32 s60, s24, 0xb0000
	s_addc_u32 s61, s25, 0
	s_add_i32 s62, s52, s38
	global_load_lds_dwordx4 v144, s[24:25]
	s_mov_b32 m0, s62
	s_nop 0
	global_load_lds_dwordx4 v140, s[60:61]
	s_add_i32 m0, s62, 0x2000
	s_nop 0
	global_load_lds_dwordx4 v144, s[60:61]
	s_mov_b32 m0, s39
	s_nop 0
	global_load_lds_dwordx4 v138, s[26:27]
	s_mov_b32 m0, s40
	s_nop 0
	global_load_lds_dwordx4 v142, s[26:27]
	s_waitcnt vmcnt(8)
	s_waitcnt lgkmcnt(0)
	s_setprio 1
	s_barrier
	v_mfma_f32_16x16x32_bf16 v[62:65], v[130:133], v[190:193], v[62:65]
	v_mfma_f32_16x16x32_bf16 v[58:61], v[154:157], v[190:193], v[58:61]
	v_mfma_f32_16x16x32_bf16 v[46:49], v[130:133], v[198:201], v[46:49]
	v_mfma_f32_16x16x32_bf16 v[42:45], v[154:157], v[198:201], v[42:45]
	v_mfma_f32_16x16x32_bf16 v[30:33], v[130:133], v[206:209], v[30:33]
	v_mfma_f32_16x16x32_bf16 v[26:29], v[154:157], v[206:209], v[26:29]
	v_mfma_f32_16x16x32_bf16 v[14:17], v[130:133], v[214:217], v[14:17]
	v_mfma_f32_16x16x32_bf16 v[10:13], v[154:157], v[214:217], v[10:13]
	v_mfma_f32_16x16x32_bf16 v[62:65], v[134:137], v[194:197], v[62:65]
	v_mfma_f32_16x16x32_bf16 v[58:61], v[166:169], v[194:197], v[58:61]
	v_mfma_f32_16x16x32_bf16 v[46:49], v[134:137], v[202:205], v[46:49]
	v_mfma_f32_16x16x32_bf16 v[42:45], v[166:169], v[202:205], v[42:45]
	v_mfma_f32_16x16x32_bf16 v[30:33], v[134:137], v[210:213], v[30:33]
	v_mfma_f32_16x16x32_bf16 v[26:29], v[166:169], v[210:213], v[26:29]
	v_mfma_f32_16x16x32_bf16 v[14:17], v[134:137], v[218:221], v[14:17]
	v_mfma_f32_16x16x32_bf16 v[10:13], v[166:169], v[218:221], v[10:13]
	v_mfma_f32_16x16x32_bf16 v[54:57], v[174:177], v[190:193], v[54:57]
	v_mfma_f32_16x16x32_bf16 v[50:53], v[182:185], v[190:193], v[50:53]
	v_mfma_f32_16x16x32_bf16 v[38:41], v[174:177], v[198:201], v[38:41]
	v_mfma_f32_16x16x32_bf16 v[34:37], v[182:185], v[198:201], v[34:37]
	v_mfma_f32_16x16x32_bf16 v[22:25], v[174:177], v[206:209], v[22:25]
	v_mfma_f32_16x16x32_bf16 v[18:21], v[182:185], v[206:209], v[18:21]
	v_mfma_f32_16x16x32_bf16 v[6:9], v[174:177], v[214:217], v[6:9]
	v_mfma_f32_16x16x32_bf16 v[2:5], v[182:185], v[214:217], v[2:5]
	v_mfma_f32_16x16x32_bf16 v[54:57], v[178:181], v[194:197], v[54:57]
	v_mfma_f32_16x16x32_bf16 v[50:53], v[186:189], v[194:197], v[50:53]
	v_mfma_f32_16x16x32_bf16 v[38:41], v[178:181], v[202:205], v[38:41]
	v_mfma_f32_16x16x32_bf16 v[34:37], v[186:189], v[202:205], v[34:37]
	v_mfma_f32_16x16x32_bf16 v[22:25], v[178:181], v[210:213], v[22:25]
	v_mfma_f32_16x16x32_bf16 v[18:21], v[186:189], v[210:213], v[18:21]
	v_mfma_f32_16x16x32_bf16 v[6:9], v[178:181], v[218:221], v[6:9]
	v_mfma_f32_16x16x32_bf16 v[2:5], v[186:189], v[218:221], v[2:5]
	s_barrier
; #define PG8_STAGE(bufoff, gbase, voff) do { _Pragma("unroll") for (int _i = 0; _i < 2; ++_i) \
;         __builtin_amdgcn_global_load_lds((const unsigned*)((const char*)(gbase) + (voff)[_i]), (LAS unsigned*)(lds + (bufoff) + ldsw + _i * 8192), 16, 0, 0); } while (0)
; #define PG8_LDA(dst, b, h) do { _Pragma("unroll") for (int m = 0; m < 4; ++m) _Pragma("unroll") for (int k = 0; k < 2; ++k) dst[m][k] = *(const LAS bf16x8*)(lds + PG8_SA(b, h) + aoff + m * 2048 + k * 1024); } while (0)
; #define PG8_LDB(dst, b, h) do { _Pragma("unroll") for (int n = 0; n < 2; ++n) _Pragma("unroll") for (int k = 0; k < 2; ++k) dst[n][k] = *(const LAS bf16x8*)(lds + PG8_SB(b, h) + boff + n * 2048 + k * 1024); } while (0)
; #define PG8_MMA(ai, bj, At, Bt) do { __builtin_amdgcn_s_setprio(1); _Pragma("unroll") for (int m = 0; m < 4; ++m) _Pragma("unroll") for (int n = 0; n < 2; ++n) _Pragma("unroll") for (int k = 0; k < 2; ++k) \
;         acc[ai][bj][m][n] = __builtin_amdgcn_mfma_f32_16x16x32_bf16(Bt[n][k], At[m][k], acc[ai][bj][m][n], 0, 0, 0); __builtin_amdgcn_s_setprio(0); } while (0)
; #define PG8_WAIT_V(n) asm volatile("s_waitcnt vmcnt(" #n ")" ::: "memory")
; #define PG8_WAIT_L(n) asm volatile("s_waitcnt lgkmcnt(" #n ")" ::: "memory")
; #define PG8_BAR __builtin_amdgcn_s_barrier()
; #define PG8_SCHED __builtin_amdgcn_sched_barrier(0)
; template <class Epi>
; __device__ __forceinline__ void gemm_phase(LAS unsigned char* lds, const Gemm g, const StaticOrder& S, const Epi& E) {
;     ...
;             PG8_LDB(B0, 1, 0); PG8_LDB(B1, 1, 1); PG8_SCHED; PG8_LDA(At, 1, 0); PG8_STAGE(PG8_SA(0, 1), a2 + hstep, voffA);
;             PG8_WAIT_V(8); PG8_WAIT_L(0); PG8_BAR; PG8_MMA(0, 0, At, B0); PG8_MMA(0, 1, At, B1); PG8_BAR; PG8_SCHED;
;             PG8_LDA(At, 1, 1); PG8_STAGE(PG8_SB(1, 0), b3, voffB); PG8_STAGE(PG8_SB(1, 1), b3 + hstep, voffB); PG8_STAGE(PG8_SA(1, 0), a3, voffA);
;             PG8_WAIT_V(8); PG8_WAIT_L(0); PG8_BAR; PG8_MMA(1, 0, At, B0); PG8_MMA(1, 1, At, B1); PG8_BAR; PG8_SCHED;
;         }
	s_setprio 0
	s_add_i32 s60, 0, 0x18000
	s_add_i32 s61, 0, 0x1c000
	v_add_u32_e32 v166, s60, v160
	v_add_u32_e32 v186, s61, v160
	ds_read_b128 v[130:133], v166
	ds_read_b128 v[134:137], v166 offset:1024
	ds_read_b128 v[154:157], v166 offset:2048
	ds_read_b128 v[166:169], v166 offset:3072
	ds_read_b128 v[174:177], v186
	ds_read_b128 v[178:181], v186 offset:1024
	ds_read_b128 v[182:185], v186 offset:2048
	ds_read_b128 v[186:189], v186 offset:3072
	s_add_u32 s26, s26, 0xb0000
	s_addc_u32 s27, s27, 0
	s_mov_b32 m0, s41
	ds_read_b128 v[190:193], v164 offset:32768
	ds_read_b128 v[194:197], v164 offset:33792
	ds_read_b128 v[198:201], v164 offset:34816
	ds_read_b128 v[202:205], v164 offset:35840
	ds_read_b128 v[206:209], v164 offset:36864
	ds_read_b128 v[210:213], v164 offset:37888
	ds_read_b128 v[214:217], v164 offset:38912
	ds_read_b128 v[218:221], v164 offset:39936
	global_load_lds_dwordx4 v138, s[26:27]
	s_mov_b32 m0, s42
	s_nop 0
	global_load_lds_dwordx4 v142, s[26:27]
	s_waitcnt vmcnt(8)
	s_waitcnt lgkmcnt(0)
	s_setprio 1
	s_barrier
	v_mfma_f32_16x16x32_bf16 v[126:129], v[130:133], v[190:193], v[126:129]
	v_mfma_f32_16x16x32_bf16 v[122:125], v[154:157], v[190:193], v[122:125]
	v_mfma_f32_16x16x32_bf16 v[110:113], v[130:133], v[198:201], v[110:113]
	v_mfma_f32_16x16x32_bf16 v[106:109], v[154:157], v[198:201], v[106:109]
	v_mfma_f32_16x16x32_bf16 v[94:97], v[130:133], v[206:209], v[94:97]
	v_mfma_f32_16x16x32_bf16 v[90:93], v[154:157], v[206:209], v[90:93]
	v_mfma_f32_16x16x32_bf16 v[78:81], v[130:133], v[214:217], v[78:81]
	v_mfma_f32_16x16x32_bf16 v[74:77], v[154:157], v[214:217], v[74:77]
	v_mfma_f32_16x16x32_bf16 v[126:129], v[134:137], v[194:197], v[126:129]
	v_mfma_f32_16x16x32_bf16 v[122:125], v[166:169], v[194:197], v[122:125]
	v_mfma_f32_16x16x32_bf16 v[110:113], v[134:137], v[202:205], v[110:113]
	v_mfma_f32_16x16x32_bf16 v[106:109], v[166:169], v[202:205], v[106:109]
	v_mfma_f32_16x16x32_bf16 v[94:97], v[134:137], v[210:213], v[94:97]
	v_mfma_f32_16x16x32_bf16 v[90:93], v[166:169], v[210:213], v[90:93]
	v_mfma_f32_16x16x32_bf16 v[78:81], v[134:137], v[218:221], v[78:81]
	v_mfma_f32_16x16x32_bf16 v[74:77], v[166:169], v[218:221], v[74:77]
	v_mfma_f32_16x16x32_bf16 v[118:121], v[174:177], v[190:193], v[118:121]
	v_mfma_f32_16x16x32_bf16 v[114:117], v[182:185], v[190:193], v[114:117]
	v_mfma_f32_16x16x32_bf16 v[102:105], v[174:177], v[198:201], v[102:105]
	v_mfma_f32_16x16x32_bf16 v[98:101], v[182:185], v[198:201], v[98:101]
	v_mfma_f32_16x16x32_bf16 v[86:89], v[174:177], v[206:209], v[86:89]
	v_mfma_f32_16x16x32_bf16 v[82:85], v[182:185], v[206:209], v[82:85]
	v_mfma_f32_16x16x32_bf16 v[70:73], v[174:177], v[214:217], v[70:73]
	v_mfma_f32_16x16x32_bf16 v[66:69], v[182:185], v[214:217], v[66:69]
	v_mfma_f32_16x16x32_bf16 v[118:121], v[178:181], v[194:197], v[118:121]
	v_mfma_f32_16x16x32_bf16 v[114:117], v[186:189], v[194:197], v[114:117]
	v_mfma_f32_16x16x32_bf16 v[102:105], v[178:181], v[202:205], v[102:105]
	v_mfma_f32_16x16x32_bf16 v[98:101], v[186:189], v[202:205], v[98:101]
	v_mfma_f32_16x16x32_bf16 v[86:89], v[178:181], v[210:213], v[86:89]
	v_mfma_f32_16x16x32_bf16 v[82:85], v[186:189], v[210:213], v[82:85]
	v_mfma_f32_16x16x32_bf16 v[70:73], v[178:181], v[218:221], v[70:73]
	v_mfma_f32_16x16x32_bf16 v[66:69], v[186:189], v[218:221], v[66:69]
	s_barrier
	s_setprio 0
	s_add_i32 s26, s60, s38
	s_mov_b32 m0, s26
	ds_read_b128 v[190:193], v164 offset:49152
	ds_read_b128 v[194:197], v164 offset:50176
	ds_read_b128 v[198:201], v164 offset:51200
	ds_read_b128 v[202:205], v164 offset:52224
	ds_read_b128 v[206:209], v164 offset:53248
	ds_read_b128 v[210:213], v164 offset:54272
	ds_read_b128 v[214:217], v164 offset:55296
	ds_read_b128 v[218:221], v164 offset:56320
	global_load_lds_dwordx4 v140, s[98:99]
	s_add_i32 m0, s26, 0x2000
	s_add_u32 s24, s24, 0xb0080
	s_addc_u32 s25, s25, 0
	s_add_i32 s26, s61, s38
	global_load_lds_dwordx4 v144, s[98:99]
	s_mov_b32 m0, s26
	s_nop 0
	global_load_lds_dwordx4 v140, s[24:25]
	s_add_i32 m0, s26, 0x2000
	s_nop 0
	global_load_lds_dwordx4 v144, s[24:25]
	s_mov_b32 m0, s44
	s_nop 0
	global_load_lds_dwordx4 v138, s[100:101]
	s_mov_b32 m0, s45
	s_nop 0
	global_load_lds_dwordx4 v142, s[100:101]
	s_waitcnt vmcnt(8)
	s_waitcnt lgkmcnt(0)
	s_setprio 1
	s_barrier
	v_mfma_f32_16x16x32_bf16 v[62:65], v[130:133], v[190:193], v[62:65]
	v_mfma_f32_16x16x32_bf16 v[58:61], v[154:157], v[190:193], v[58:61]
	v_mfma_f32_16x16x32_bf16 v[46:49], v[130:133], v[198:201], v[46:49]
	v_mfma_f32_16x16x32_bf16 v[42:45], v[154:157], v[198:201], v[42:45]
	v_mfma_f32_16x16x32_bf16 v[30:33], v[130:133], v[206:209], v[30:33]
	v_mfma_f32_16x16x32_bf16 v[26:29], v[154:157], v[206:209], v[26:29]
	v_mfma_f32_16x16x32_bf16 v[14:17], v[130:133], v[214:217], v[14:17]
	v_mfma_f32_16x16x32_bf16 v[10:13], v[154:157], v[214:217], v[10:13]
	v_mfma_f32_16x16x32_bf16 v[62:65], v[134:137], v[194:197], v[62:65]
	v_mfma_f32_16x16x32_bf16 v[58:61], v[166:169], v[194:197], v[58:61]
	v_mfma_f32_16x16x32_bf16 v[46:49], v[134:137], v[202:205], v[46:49]
	v_mfma_f32_16x16x32_bf16 v[42:45], v[166:169], v[202:205], v[42:45]
	v_mfma_f32_16x16x32_bf16 v[30:33], v[134:137], v[210:213], v[30:33]
	v_mfma_f32_16x16x32_bf16 v[26:29], v[166:169], v[210:213], v[26:29]
	v_mfma_f32_16x16x32_bf16 v[14:17], v[134:137], v[218:221], v[14:17]
	v_mfma_f32_16x16x32_bf16 v[10:13], v[166:169], v[218:221], v[10:13]
	v_mfma_f32_16x16x32_bf16 v[54:57], v[174:177], v[190:193], v[54:57]
	v_mfma_f32_16x16x32_bf16 v[50:53], v[182:185], v[190:193], v[50:53]
	v_mfma_f32_16x16x32_bf16 v[38:41], v[174:177], v[198:201], v[38:41]
	v_mfma_f32_16x16x32_bf16 v[34:37], v[182:185], v[198:201], v[34:37]
	v_mfma_f32_16x16x32_bf16 v[22:25], v[174:177], v[206:209], v[22:25]
	v_mfma_f32_16x16x32_bf16 v[18:21], v[182:185], v[206:209], v[18:21]
	v_mfma_f32_16x16x32_bf16 v[6:9], v[174:177], v[214:217], v[6:9]
	v_mfma_f32_16x16x32_bf16 v[2:5], v[182:185], v[214:217], v[2:5]
	v_mfma_f32_16x16x32_bf16 v[54:57], v[178:181], v[194:197], v[54:57]
	v_mfma_f32_16x16x32_bf16 v[50:53], v[186:189], v[194:197], v[50:53]
	v_mfma_f32_16x16x32_bf16 v[38:41], v[178:181], v[202:205], v[38:41]
	v_mfma_f32_16x16x32_bf16 v[34:37], v[186:189], v[202:205], v[34:37]
	v_mfma_f32_16x16x32_bf16 v[22:25], v[178:181], v[210:213], v[22:25]
	v_mfma_f32_16x16x32_bf16 v[18:21], v[186:189], v[210:213], v[18:21]
	v_mfma_f32_16x16x32_bf16 v[6:9], v[178:181], v[218:221], v[6:9]
	v_mfma_f32_16x16x32_bf16 v[2:5], v[186:189], v[218:221], v[2:5]
	s_barrier
	s_setprio 0
	s_add_i32 s59, s59, 2
	s_add_u32 s22, s22, 0x100
	s_addc_u32 s23, s23, 0
	s_add_u32 s57, s57, 0x100
	s_addc_u32 s58, s58, 0
	s_cmp_gt_u32 s59, 41
	s_cbranch_scc0 .LBB0_971
	s_and_b64 vcc, exec, s[18:19]
	s_cbranch_vccz .LBB0_974
	s_barrier
